# lane-transposed epilogue stores, bpermute pipelined 2 deep through a register pool, Zm and gate GEMMs
# baseline (speedup 1.0000x reference)
; #define PG8_STAGE(bufoff, gbase, voff) do { _Pragma("unroll") for (int _i = 0; _i < 2; ++_i) \
;         __builtin_amdgcn_global_load_lds((const unsigned*)((const char*)(gbase) + (voff)[_i]), (LAS unsigned*)(lds + (bufoff) + ldsw + _i * 8192), 16, 0, 0); } while (0)
; #define PG8_LDA(dst, b, h) do { _Pragma("unroll") for (int m = 0; m < 4; ++m) _Pragma("unroll") for (int k = 0; k < 2; ++k) dst[m][k] = *(const LAS bf16x8*)(lds + PG8_SA(b, h) + aoff + m * 2048 + k * 1024); } while (0)
; #define PG8_LDB(dst, b, h) do { _Pragma("unroll") for (int n = 0; n < 2; ++n) _Pragma("unroll") for (int k = 0; k < 2; ++k) dst[n][k] = *(const LAS bf16x8*)(lds + PG8_SB(b, h) + boff + n * 2048 + k * 1024); } while (0)
; #define PG8_MMA(ai, bj, At, Bt) do { __builtin_amdgcn_s_setprio(1); _Pragma("unroll") for (int m = 0; m < 4; ++m) _Pragma("unroll") for (int n = 0; n < 2; ++n) _Pragma("unroll") for (int k = 0; k < 2; ++k) \
;         acc[ai][bj][m][n] = __builtin_amdgcn_mfma_f32_16x16x32_bf16(Bt[n][k], At[m][k], acc[ai][bj][m][n], 0, 0, 0); __builtin_amdgcn_s_setprio(0); } while (0)
; #define PG8_WAIT_V(n) asm volatile("s_waitcnt vmcnt(" #n ")" ::: "memory")
; #define PG8_WAIT_L(n) asm volatile("s_waitcnt lgkmcnt(" #n ")" ::: "memory")
; #define PG8_BAR __builtin_amdgcn_s_barrier()
; #define PG8_SCHED __builtin_amdgcn_sched_barrier(0)
; template <class Epi>
; DEVI void gemm_phase(const int wv, LAS unsigned char* lds, const Gemm g, const Order& S, const Epi& E) {
;     ...
;             PG8_LDB(B0, 0, 0); PG8_SCHED; PG8_LDA(At, 0, 0); PG8_STAGE(PG8_SA(1, 1), a1 + hstepA, voffA);
;             PG8_WAIT_L(8); PG8_BAR; PG8_WAIT_L(0); PG8_MMA(0, 0, At, B0); PG8_BAR; PG8_SCHED;
;             PG8_LDB(B1, 0, 1); PG8_STAGE(PG8_SB(0, 0), b2, voffB);
;             PG8_BAR; PG8_WAIT_L(0); PG8_MMA(0, 1, At, B1); PG8_BAR;
;             PG8_LDA(At, 0, 1); PG8_STAGE(PG8_SA(0, 0), a2, voffA);
;             PG8_BAR; PG8_WAIT_L(0); PG8_MMA(1, 0, At, B0); PG8_BAR; PG8_SCHED;
;             PG8_STAGE(PG8_SB(0, 1), b2 + hstepB, voffB);
;             PG8_WAIT_V(6); PG8_BAR; PG8_MMA(1, 1, At, B1); PG8_BAR;
.LBB0_287:
	s_add_u32 s30, s28, 0xfffc0080
	s_addc_u32 s31, s29, -1
	s_add_i32 s61, 0, 0x10000
	v_add_u32_e32 v156, s61, v145
	ds_read_b128 v[140:143], v156
	ds_read_b128 v[148:151], v156 offset:1024
	ds_read_b128 v[152:155], v156 offset:2048
	ds_read_b128 v[156:159], v156 offset:3072
	s_cmp_eq_u32 s60, 12
	s_cselect_b32 s37, s7, s31
	s_cselect_b32 s36, s56, s30
	s_cselect_b32 s31, s5, s59
	s_cselect_b32 s30, s57, s58
	v_lshl_add_u64 v[192:193], s[28:29], 0, v[136:137]
	s_add_i32 m0, s1, 0xc000
	ds_read_b128 v[160:163], v147
	ds_read_b128 v[164:167], v147 offset:1024
	ds_read_b128 v[168:171], v147 offset:2048
	ds_read_b128 v[172:175], v147 offset:3072
	ds_read_b128 v[176:179], v147 offset:4096
	ds_read_b128 v[180:183], v147 offset:5120
	ds_read_b128 v[184:187], v147 offset:6144
	ds_read_b128 v[188:191], v147 offset:7168
	global_load_lds_dwordx4 v[192:193], off
	v_lshl_add_u64 v[192:193], s[28:29], 0, v[138:139]
	s_add_i32 m0, s1, 0xe000
	s_nop 0
	global_load_lds_dwordx4 v[192:193], off
	s_waitcnt lgkmcnt(8)
	s_barrier
	s_waitcnt lgkmcnt(0)
	s_setprio 1
	s_waitcnt lgkmcnt(0)
	v_mfma_f32_16x16x32_bf16 v[126:129], v[140:143], v[160:163], v[126:129]
	v_mfma_f32_16x16x32_bf16 v[122:125], v[152:155], v[160:163], v[122:125]
	v_mfma_f32_16x16x32_bf16 v[118:121], v[140:143], v[168:171], v[118:121]
	v_mfma_f32_16x16x32_bf16 v[110:113], v[152:155], v[168:171], v[110:113]
	v_mfma_f32_16x16x32_bf16 v[102:105], v[140:143], v[176:179], v[102:105]
	v_mfma_f32_16x16x32_bf16 v[94:97], v[152:155], v[176:179], v[94:97]
	v_mfma_f32_16x16x32_bf16 v[86:89], v[140:143], v[184:187], v[86:89]
	v_mfma_f32_16x16x32_bf16 v[78:81], v[152:155], v[184:187], v[78:81]
	v_mfma_f32_16x16x32_bf16 v[126:129], v[148:151], v[164:167], v[126:129]
	v_mfma_f32_16x16x32_bf16 v[122:125], v[156:159], v[164:167], v[122:125]
	v_mfma_f32_16x16x32_bf16 v[118:121], v[148:151], v[172:175], v[118:121]
	v_mfma_f32_16x16x32_bf16 v[110:113], v[156:159], v[172:175], v[110:113]
	v_mfma_f32_16x16x32_bf16 v[102:105], v[148:151], v[180:183], v[102:105]
	v_mfma_f32_16x16x32_bf16 v[94:97], v[156:159], v[180:183], v[94:97]
	v_mfma_f32_16x16x32_bf16 v[86:89], v[148:151], v[188:191], v[86:89]
	v_mfma_f32_16x16x32_bf16 v[78:81], v[156:159], v[188:191], v[78:81]
	s_setprio 0
	s_barrier
	s_add_i32 s64, 0, 0x14000
	s_add_i32 s61, s61, s95
	v_add_u32_e32 v199, s64, v145
	v_lshl_add_u64 v[212:213], s[30:31], 0, v[0:1]
	s_mov_b32 m0, s61
	ds_read_b128 v[192:195], v199
	ds_read_b128 v[200:203], v199 offset:1024
	ds_read_b128 v[204:207], v199 offset:2048
	ds_read_b128 v[208:211], v199 offset:3072
	global_load_lds_dwordx4 v[212:213], off
	v_lshl_add_u64 v[214:215], s[30:31], 0, v[134:135]
	s_add_i32 m0, s61, 0x2000
	s_nop 0
	global_load_lds_dwordx4 v[214:215], off
	s_barrier
	s_waitcnt lgkmcnt(0)
	s_setprio 1
	s_waitcnt lgkmcnt(0)
	v_mfma_f32_16x16x32_bf16 v[114:117], v[192:195], v[160:163], v[114:117]
	v_mfma_f32_16x16x32_bf16 v[106:109], v[204:207], v[160:163], v[106:109]
	v_mfma_f32_16x16x32_bf16 v[98:101], v[192:195], v[168:171], v[98:101]
	v_mfma_f32_16x16x32_bf16 v[90:93], v[204:207], v[168:171], v[90:93]
	v_mfma_f32_16x16x32_bf16 v[82:85], v[192:195], v[176:179], v[82:85]
	v_mfma_f32_16x16x32_bf16 v[74:77], v[204:207], v[176:179], v[74:77]
	v_mfma_f32_16x16x32_bf16 v[70:73], v[192:195], v[184:187], v[70:73]
	v_mfma_f32_16x16x32_bf16 v[66:69], v[204:207], v[184:187], v[66:69]
	v_mfma_f32_16x16x32_bf16 v[114:117], v[200:203], v[164:167], v[114:117]
	v_mfma_f32_16x16x32_bf16 v[106:109], v[208:211], v[164:167], v[106:109]
	v_mfma_f32_16x16x32_bf16 v[98:101], v[200:203], v[172:175], v[98:101]
	v_mfma_f32_16x16x32_bf16 v[90:93], v[208:211], v[172:175], v[90:93]
	v_mfma_f32_16x16x32_bf16 v[82:85], v[200:203], v[180:183], v[82:85]
	v_mfma_f32_16x16x32_bf16 v[74:77], v[208:211], v[180:183], v[74:77]
	v_mfma_f32_16x16x32_bf16 v[70:73], v[200:203], v[188:191], v[70:73]
	v_mfma_f32_16x16x32_bf16 v[66:69], v[208:211], v[188:191], v[66:69]
	s_setprio 0
	s_mov_b32 m0, s1
	v_lshl_add_u64 v[216:217], s[36:37], 0, v[130:131]
	s_barrier
	ds_read_b128 v[160:163], v147 offset:16384
	ds_read_b128 v[164:167], v147 offset:17408
	ds_read_b128 v[168:171], v147 offset:18432
	ds_read_b128 v[172:175], v147 offset:19456
	ds_read_b128 v[176:179], v147 offset:20480
	ds_read_b128 v[180:183], v147 offset:21504
	ds_read_b128 v[184:187], v147 offset:22528
	ds_read_b128 v[188:191], v147 offset:23552
	global_load_lds_dwordx4 v[216:217], off
	v_lshl_add_u64 v[218:219], s[36:37], 0, v[132:133]
	s_mov_b32 m0, s3
	s_nop 0
	global_load_lds_dwordx4 v[218:219], off
	s_barrier
	s_waitcnt lgkmcnt(0)
	s_setprio 1
	s_waitcnt lgkmcnt(0)
	v_mfma_f32_16x16x32_bf16 v[62:65], v[140:143], v[160:163], v[62:65]
	v_mfma_f32_16x16x32_bf16 v[58:61], v[152:155], v[160:163], v[58:61]
	v_mfma_f32_16x16x32_bf16 v[54:57], v[140:143], v[168:171], v[54:57]
	v_mfma_f32_16x16x32_bf16 v[46:49], v[152:155], v[168:171], v[46:49]
	v_mfma_f32_16x16x32_bf16 v[38:41], v[140:143], v[176:179], v[38:41]
	v_mfma_f32_16x16x32_bf16 v[30:33], v[152:155], v[176:179], v[30:33]
	v_mfma_f32_16x16x32_bf16 v[22:25], v[140:143], v[184:187], v[22:25]
	v_mfma_f32_16x16x32_bf16 v[14:17], v[152:155], v[184:187], v[14:17]
	v_mfma_f32_16x16x32_bf16 v[62:65], v[148:151], v[164:167], v[62:65]
	v_mfma_f32_16x16x32_bf16 v[58:61], v[156:159], v[164:167], v[58:61]
	v_mfma_f32_16x16x32_bf16 v[54:57], v[148:151], v[172:175], v[54:57]
	v_mfma_f32_16x16x32_bf16 v[46:49], v[156:159], v[172:175], v[46:49]
	v_mfma_f32_16x16x32_bf16 v[38:41], v[148:151], v[180:183], v[38:41]
	v_mfma_f32_16x16x32_bf16 v[30:33], v[156:159], v[180:183], v[30:33]
	v_mfma_f32_16x16x32_bf16 v[22:25], v[148:151], v[188:191], v[22:25]
	v_mfma_f32_16x16x32_bf16 v[14:17], v[156:159], v[188:191], v[14:17]
	s_setprio 0
	s_barrier
; #define PG8_STAGE(bufoff, gbase, voff) do { _Pragma("unroll") for (int _i = 0; _i < 2; ++_i) \
;         __builtin_amdgcn_global_load_lds((const unsigned*)((const char*)(gbase) + (voff)[_i]), (LAS unsigned*)(lds + (bufoff) + ldsw + _i * 8192), 16, 0, 0); } while (0)
; #define PG8_LDA(dst, b, h) do { _Pragma("unroll") for (int m = 0; m < 4; ++m) _Pragma("unroll") for (int k = 0; k < 2; ++k) dst[m][k] = *(const LAS bf16x8*)(lds + PG8_SA(b, h) + aoff + m * 2048 + k * 1024); } while (0)
; #define PG8_LDB(dst, b, h) do { _Pragma("unroll") for (int n = 0; n < 2; ++n) _Pragma("unroll") for (int k = 0; k < 2; ++k) dst[n][k] = *(const LAS bf16x8*)(lds + PG8_SB(b, h) + boff + n * 2048 + k * 1024); } while (0)
; #define PG8_MMA(ai, bj, At, Bt) do { __builtin_amdgcn_s_setprio(1); _Pragma("unroll") for (int m = 0; m < 4; ++m) _Pragma("unroll") for (int n = 0; n < 2; ++n) _Pragma("unroll") for (int k = 0; k < 2; ++k) \
;         acc[ai][bj][m][n] = __builtin_amdgcn_mfma_f32_16x16x32_bf16(Bt[n][k], At[m][k], acc[ai][bj][m][n], 0, 0, 0); __builtin_amdgcn_s_setprio(0); } while (0)
; #define PG8_WAIT_V(n) asm volatile("s_waitcnt vmcnt(" #n ")" ::: "memory")
; #define PG8_WAIT_L(n) asm volatile("s_waitcnt lgkmcnt(" #n ")" ::: "memory")
; #define PG8_BAR __builtin_amdgcn_s_barrier()
; #define PG8_SCHED __builtin_amdgcn_sched_barrier(0)
; template <class Epi>
; DEVI void gemm_phase(const int wv, LAS unsigned char* lds, const Gemm g, const Order& S, const Epi& E) {
;     ...
;             PG8_WAIT_V(6); PG8_BAR; PG8_MMA(1, 1, At, B1); PG8_BAR;
;             PG8_LDB(B0, 1, 0); PG8_SCHED; PG8_LDA(At, 1, 0); PG8_STAGE(PG8_SA(0, 1), a2 + hstepA, voffA);
;             PG8_WAIT_L(8); PG8_BAR; PG8_WAIT_L(0); PG8_MMA(0, 0, At, B0); PG8_BAR; PG8_SCHED;
;             PG8_LDB(B1, 1, 1); PG8_STAGE(PG8_SB(1, 0), b3, voffB);
;             PG8_BAR; PG8_WAIT_L(0); PG8_MMA(0, 1, At, B1); PG8_BAR;
;             PG8_LDA(At, 1, 1); PG8_STAGE(PG8_SA(1, 0), a3, voffA);
;             PG8_BAR; PG8_WAIT_L(0); PG8_MMA(1, 0, At, B0); PG8_BAR; PG8_SCHED;
	s_add_u32 s62, s30, 0x40000
	s_addc_u32 s63, s31, 0
	s_add_i32 s61, s64, s95
	v_lshl_add_u64 v[140:141], s[62:63], 0, v[0:1]
	s_mov_b32 m0, s61
	s_nop 0
	global_load_lds_dwordx4 v[140:141], off
	v_lshl_add_u64 v[140:141], s[62:63], 0, v[134:135]
	s_add_i32 m0, s61, 0x2000
	s_nop 0
	global_load_lds_dwordx4 v[140:141], off
	s_waitcnt vmcnt(6)
	s_barrier
	s_setprio 1
	v_mfma_f32_16x16x32_bf16 v[50:53], v[192:195], v[160:163], v[50:53]
	v_mfma_f32_16x16x32_bf16 v[42:45], v[204:207], v[160:163], v[42:45]
	v_mfma_f32_16x16x32_bf16 v[34:37], v[192:195], v[168:171], v[34:37]
	v_mfma_f32_16x16x32_bf16 v[26:29], v[204:207], v[168:171], v[26:29]
	v_mfma_f32_16x16x32_bf16 v[18:21], v[192:195], v[176:179], v[18:21]
	v_mfma_f32_16x16x32_bf16 v[10:13], v[204:207], v[176:179], v[10:13]
	v_mfma_f32_16x16x32_bf16 v[6:9], v[192:195], v[184:187], v[6:9]
	v_mfma_f32_16x16x32_bf16 v[2:5], v[204:207], v[184:187], v[2:5]
	v_mfma_f32_16x16x32_bf16 v[50:53], v[200:203], v[164:167], v[50:53]
	v_mfma_f32_16x16x32_bf16 v[42:45], v[208:211], v[164:167], v[42:45]
	v_mfma_f32_16x16x32_bf16 v[34:37], v[200:203], v[172:175], v[34:37]
	v_mfma_f32_16x16x32_bf16 v[26:29], v[208:211], v[172:175], v[26:29]
	v_mfma_f32_16x16x32_bf16 v[18:21], v[200:203], v[180:183], v[18:21]
	v_mfma_f32_16x16x32_bf16 v[10:13], v[208:211], v[180:183], v[10:13]
	v_mfma_f32_16x16x32_bf16 v[6:9], v[200:203], v[188:191], v[6:9]
	v_mfma_f32_16x16x32_bf16 v[2:5], v[208:211], v[188:191], v[2:5]
	s_setprio 0
	s_add_i32 s61, 0, 0x18000
	v_add_u32_e32 v156, s61, v145
	s_barrier
	ds_read_b128 v[140:143], v156
	ds_read_b128 v[148:151], v156 offset:1024
	ds_read_b128 v[152:155], v156 offset:2048
	ds_read_b128 v[156:159], v156 offset:3072
	s_add_u32 s36, s36, 0x40000
	s_addc_u32 s37, s37, 0
	s_mov_b32 m0, s41
	v_lshl_add_u64 v[192:193], s[36:37], 0, v[130:131]
	ds_read_b128 v[160:163], v147 offset:32768
	ds_read_b128 v[164:167], v147 offset:33792
	ds_read_b128 v[168:171], v147 offset:34816
	ds_read_b128 v[172:175], v147 offset:35840
	ds_read_b128 v[176:179], v147 offset:36864
	ds_read_b128 v[180:183], v147 offset:37888
	ds_read_b128 v[184:187], v147 offset:38912
	ds_read_b128 v[188:191], v147 offset:39936
	global_load_lds_dwordx4 v[192:193], off
	v_lshl_add_u64 v[192:193], s[36:37], 0, v[132:133]
	s_mov_b32 m0, s50
	s_nop 0
	global_load_lds_dwordx4 v[192:193], off
	s_waitcnt lgkmcnt(8)
	s_barrier
	s_waitcnt lgkmcnt(0)
	s_setprio 1
	s_waitcnt lgkmcnt(0)
	v_mfma_f32_16x16x32_bf16 v[126:129], v[140:143], v[160:163], v[126:129]
	v_mfma_f32_16x16x32_bf16 v[122:125], v[152:155], v[160:163], v[122:125]
	v_mfma_f32_16x16x32_bf16 v[118:121], v[140:143], v[168:171], v[118:121]
	v_mfma_f32_16x16x32_bf16 v[110:113], v[152:155], v[168:171], v[110:113]
	v_mfma_f32_16x16x32_bf16 v[102:105], v[140:143], v[176:179], v[102:105]
	v_mfma_f32_16x16x32_bf16 v[94:97], v[152:155], v[176:179], v[94:97]
	v_mfma_f32_16x16x32_bf16 v[86:89], v[140:143], v[184:187], v[86:89]
	v_mfma_f32_16x16x32_bf16 v[78:81], v[152:155], v[184:187], v[78:81]
	v_mfma_f32_16x16x32_bf16 v[126:129], v[148:151], v[164:167], v[126:129]
	v_mfma_f32_16x16x32_bf16 v[122:125], v[156:159], v[164:167], v[122:125]
	v_mfma_f32_16x16x32_bf16 v[118:121], v[148:151], v[172:175], v[118:121]
	v_mfma_f32_16x16x32_bf16 v[110:113], v[156:159], v[172:175], v[110:113]
	v_mfma_f32_16x16x32_bf16 v[102:105], v[148:151], v[180:183], v[102:105]
	v_mfma_f32_16x16x32_bf16 v[94:97], v[156:159], v[180:183], v[94:97]
	v_mfma_f32_16x16x32_bf16 v[86:89], v[148:151], v[188:191], v[86:89]
	v_mfma_f32_16x16x32_bf16 v[78:81], v[156:159], v[188:191], v[78:81]
	s_setprio 0
	s_barrier
	s_add_i32 s36, 0, 0x1c000
	s_add_i32 s37, s61, s95
	v_add_u32_e32 v199, s36, v145
	v_lshl_add_u64 v[212:213], v[212:213], 0, s[92:93]
	s_mov_b32 m0, s37
	ds_read_b128 v[192:195], v199
	ds_read_b128 v[200:203], v199 offset:1024
	ds_read_b128 v[204:207], v199 offset:2048
	ds_read_b128 v[208:211], v199 offset:3072
	global_load_lds_dwordx4 v[212:213], off
	v_lshl_add_u64 v[212:213], v[214:215], 0, s[92:93]
	s_add_i32 m0, s37, 0x2000
	s_nop 0
	global_load_lds_dwordx4 v[212:213], off
	s_barrier
	s_waitcnt lgkmcnt(0)
	s_setprio 1
	s_waitcnt lgkmcnt(0)
	v_mfma_f32_16x16x32_bf16 v[114:117], v[192:195], v[160:163], v[114:117]
	v_mfma_f32_16x16x32_bf16 v[106:109], v[204:207], v[160:163], v[106:109]
	v_mfma_f32_16x16x32_bf16 v[98:101], v[192:195], v[168:171], v[98:101]
	v_mfma_f32_16x16x32_bf16 v[90:93], v[204:207], v[168:171], v[90:93]
	v_mfma_f32_16x16x32_bf16 v[82:85], v[192:195], v[176:179], v[82:85]
	v_mfma_f32_16x16x32_bf16 v[74:77], v[204:207], v[176:179], v[74:77]
	v_mfma_f32_16x16x32_bf16 v[70:73], v[192:195], v[184:187], v[70:73]
	v_mfma_f32_16x16x32_bf16 v[66:69], v[204:207], v[184:187], v[66:69]
	v_mfma_f32_16x16x32_bf16 v[114:117], v[200:203], v[164:167], v[114:117]
	v_mfma_f32_16x16x32_bf16 v[106:109], v[208:211], v[164:167], v[106:109]
	v_mfma_f32_16x16x32_bf16 v[98:101], v[200:203], v[172:175], v[98:101]
	v_mfma_f32_16x16x32_bf16 v[90:93], v[208:211], v[172:175], v[90:93]
	v_mfma_f32_16x16x32_bf16 v[82:85], v[200:203], v[180:183], v[82:85]
	v_mfma_f32_16x16x32_bf16 v[74:77], v[208:211], v[180:183], v[74:77]
	v_mfma_f32_16x16x32_bf16 v[70:73], v[200:203], v[188:191], v[70:73]
	v_mfma_f32_16x16x32_bf16 v[66:69], v[208:211], v[188:191], v[66:69]
	s_setprio 0
	s_mov_b32 m0, s51
	v_lshl_add_u64 v[212:213], v[216:217], 0, s[92:93]
	s_barrier
	ds_read_b128 v[160:163], v147 offset:49152
	ds_read_b128 v[164:167], v147 offset:50176
	ds_read_b128 v[168:171], v147 offset:51200
	ds_read_b128 v[172:175], v147 offset:52224
	ds_read_b128 v[176:179], v147 offset:53248
	ds_read_b128 v[180:183], v147 offset:54272
	ds_read_b128 v[184:187], v147 offset:55296
	ds_read_b128 v[188:191], v147 offset:56320
	global_load_lds_dwordx4 v[212:213], off
	v_lshl_add_u64 v[212:213], v[218:219], 0, s[92:93]
	s_mov_b32 m0, s52
	s_nop 0
	global_load_lds_dwordx4 v[212:213], off
	s_barrier
; DEVI unsigned cvt_pk_bf16(float lo, float hi) { unsigned r; asm volatile("v_cvt_pk_bf16_f32 %0, %1, %2" : "=v"(r) : "v"(lo), "v"(hi)); return r; }
; #define PG8_WAIT_V(n) asm volatile("s_waitcnt vmcnt(" #n ")" ::: "memory")
; #define PG8_WAIT_L(n) asm volatile("s_waitcnt lgkmcnt(" #n ")" ::: "memory")
; #define PG8_BAR __builtin_amdgcn_s_barrier()
;     DEVI void operator()(f32x4 (&acc)[2][2][4][2], const Unit& u, int wr, int wc, int fr, int fq) const {
;     ...
;             for (int m = 0; m < 4; ++m) { bf16_t* rowp = O + (size_t)(row0 + ai * HALF + m * 16) * ldc + col0;
;                 float rstd = 1.0f; if (RS) rstd = rsqrtf(ssq[row0 + ai * HALF + m * 16] * (1.0f / 1024.0f) + EPS);
; #pragma unroll
;                 for (int bj = 0; bj < 2; ++bj) { f32x4 v0 = acc[ai][bj][m][0], v1 = acc[ai][bj][m][1];
;                     if (RS) { v0 = v0 * rstd + sh[bj][0]; v1 = v1 * rstd + sh[bj][1]; }
;                     if (ACT == 1) {
; #pragma unroll
;                         for (int j = 0; j < 4; ++j) { const float a = fmaxf(v0[j], 0.f), b = fmaxf(v1[j], 0.f); v0[j] = a * a; v1[j] = b * b; } }
;                     if (ACT == 2) {
; #pragma unroll
;                         for (int j = 0; j < 4; ++j) { v0[j] = 1.0f + __expf(-fminf(fmaxf(v0[j], -30.f), 30.f)); v1[j] = 1.0f + __expf(-fminf(fmaxf(v1[j], -30.f), 30.f)); } }
;                     u32x4 w; w.x = cvt_pk_bf16(v0[0], v0[1]); w.y = cvt_pk_bf16(v0[2], v0[3]); w.z = cvt_pk_bf16(v1[0], v1[1]); w.w = cvt_pk_bf16(v1[2], v1[3]);
;                     *(u32x4*)(rowp + bj * HALF) = w; } }
; template <class Epi>
; DEVI void gemm_phase(const int wv, LAS unsigned char* lds, const Gemm g, const Order& S, const Epi& E) {
;     ...
;             PG8_WAIT_V(6); PG8_BAR; PG8_MMA(1, 1, At, B1); PG8_BAR;
;             PG8_LDB(B0, 1, 0); PG8_SCHED; PG8_LDA(At, 1, 0); PG8_STAGE(PG8_SA(0, 1), a2 + hstepA, voffA);
;             PG8_WAIT_L(8); PG8_BAR; PG8_WAIT_L(0); PG8_MMA(0, 0, At, B0); PG8_BAR; PG8_SCHED;
;             PG8_LDB(B1, 1, 1); PG8_STAGE(PG8_SB(1, 0), b3, voffB);
;             PG8_BAR; PG8_WAIT_L(0); PG8_MMA(0, 1, At, B1); PG8_BAR;
;             PG8_LDA(At, 1, 1); PG8_STAGE(PG8_SA(1, 0), a3, voffA);
;             PG8_BAR; PG8_WAIT_L(0); PG8_MMA(1, 0, At, B0); PG8_BAR; PG8_SCHED;
;             PG8_STAGE(PG8_SB(1, 1), b3 + hstepB, voffB);
;             PG8_WAIT_V(6); PG8_BAR; PG8_MMA(1, 1, At, B1); PG8_BAR;
;         }
	s_waitcnt lgkmcnt(0)
	s_setprio 1
	s_waitcnt lgkmcnt(0)
	v_mfma_f32_16x16x32_bf16 v[62:65], v[140:143], v[160:163], v[62:65]
	v_mfma_f32_16x16x32_bf16 v[58:61], v[152:155], v[160:163], v[58:61]
	v_mfma_f32_16x16x32_bf16 v[54:57], v[140:143], v[168:171], v[54:57]
	v_mfma_f32_16x16x32_bf16 v[46:49], v[152:155], v[168:171], v[46:49]
	v_mfma_f32_16x16x32_bf16 v[38:41], v[140:143], v[176:179], v[38:41]
	v_mfma_f32_16x16x32_bf16 v[30:33], v[152:155], v[176:179], v[30:33]
	v_mfma_f32_16x16x32_bf16 v[22:25], v[140:143], v[184:187], v[22:25]
	v_mfma_f32_16x16x32_bf16 v[14:17], v[152:155], v[184:187], v[14:17]
	v_mfma_f32_16x16x32_bf16 v[62:65], v[148:151], v[164:167], v[62:65]
	v_mfma_f32_16x16x32_bf16 v[58:61], v[156:159], v[164:167], v[58:61]
	v_mfma_f32_16x16x32_bf16 v[54:57], v[148:151], v[172:175], v[54:57]
	v_mfma_f32_16x16x32_bf16 v[46:49], v[156:159], v[172:175], v[46:49]
	v_mfma_f32_16x16x32_bf16 v[38:41], v[148:151], v[180:183], v[38:41]
	v_mfma_f32_16x16x32_bf16 v[30:33], v[156:159], v[180:183], v[30:33]
	v_mfma_f32_16x16x32_bf16 v[22:25], v[148:151], v[188:191], v[22:25]
	v_mfma_f32_16x16x32_bf16 v[14:17], v[156:159], v[188:191], v[14:17]
	s_setprio 0
	s_barrier
	s_add_u32 s30, s30, 0x40080
	s_addc_u32 s31, s31, 0
	s_add_i32 s36, s36, s95
	v_lshl_add_u64 v[140:141], s[30:31], 0, v[0:1]
	s_mov_b32 m0, s36
	s_nop 0
	global_load_lds_dwordx4 v[140:141], off
	v_lshl_add_u64 v[140:141], s[30:31], 0, v[134:135]
	s_add_i32 m0, s36, 0x2000
	s_nop 0
	global_load_lds_dwordx4 v[140:141], off
	s_waitcnt vmcnt(6)
	s_barrier
	s_setprio 1
	v_mfma_f32_16x16x32_bf16 v[50:53], v[192:195], v[160:163], v[50:53]
	v_mfma_f32_16x16x32_bf16 v[42:45], v[204:207], v[160:163], v[42:45]
	v_mfma_f32_16x16x32_bf16 v[34:37], v[192:195], v[168:171], v[34:37]
	v_mfma_f32_16x16x32_bf16 v[26:29], v[204:207], v[168:171], v[26:29]
	v_mfma_f32_16x16x32_bf16 v[18:21], v[192:195], v[176:179], v[18:21]
	v_mfma_f32_16x16x32_bf16 v[10:13], v[204:207], v[176:179], v[10:13]
	v_mfma_f32_16x16x32_bf16 v[6:9], v[192:195], v[184:187], v[6:9]
	v_mfma_f32_16x16x32_bf16 v[2:5], v[204:207], v[184:187], v[2:5]
	v_mfma_f32_16x16x32_bf16 v[50:53], v[200:203], v[164:167], v[50:53]
	v_mfma_f32_16x16x32_bf16 v[42:45], v[208:211], v[164:167], v[42:45]
	v_mfma_f32_16x16x32_bf16 v[34:37], v[200:203], v[172:175], v[34:37]
	v_mfma_f32_16x16x32_bf16 v[26:29], v[208:211], v[172:175], v[26:29]
	v_mfma_f32_16x16x32_bf16 v[18:21], v[200:203], v[180:183], v[18:21]
	v_mfma_f32_16x16x32_bf16 v[10:13], v[208:211], v[180:183], v[10:13]
	v_mfma_f32_16x16x32_bf16 v[6:9], v[200:203], v[188:191], v[6:9]
	v_mfma_f32_16x16x32_bf16 v[2:5], v[208:211], v[188:191], v[2:5]
	s_setprio 0
	s_add_i32 s60, s60, 2
	s_add_u32 s28, s28, 0x100
	s_addc_u32 s29, s29, 0
	s_add_u32 s58, s58, 0x100
	s_addc_u32 s59, s59, 0
	s_cmp_gt_u32 s60, 13
	s_barrier
	s_cbranch_scc0 .LBB0_287
	v_lshl_or_b32 v142, s0, 8, v146
	v_lshl_add_u32 v150, s2, 8, v144
	v_ashrrev_i32_e32 v143, 31, v142
	v_mov_b64_e32 v[140:141], s[24:25]
	v_mad_i64_i32 v[148:149], s[28:29], v150, s46, v[140:141]
	v_lshlrev_b64 v[142:143], 1, v[142:143]
	v_lshl_add_u64 v[148:149], v[148:149], 0, v[142:143]
	v_cvt_pk_bf16_f32 v126, v126, v127
	v_cvt_pk_bf16_f32 v127, v128, v129
	v_cvt_pk_bf16_f32 v128, v122, v123
	v_cvt_pk_bf16_f32 v129, v124, v125
	ds_bpermute_b32 v160, v254, v126
	ds_bpermute_b32 v161, v254, v127
	ds_bpermute_b32 v162, v254, v128
	ds_bpermute_b32 v163, v254, v129
	v_mov_b64_e32 v[176:177], v[148:149]
	v_cvt_pk_bf16_f32 v114, v114, v115
	v_cvt_pk_bf16_f32 v115, v116, v117
	v_cvt_pk_bf16_f32 v116, v106, v107
	v_or_b32_e32 v106, 16, v150
	v_mad_i64_i32 v[106:107], s[28:29], v106, s46, v[140:141]
	v_cvt_pk_bf16_f32 v117, v108, v109
	ds_bpermute_b32 v164, v254, v114
	ds_bpermute_b32 v165, v254, v115
	ds_bpermute_b32 v166, v254, v116
	ds_bpermute_b32 v167, v254, v117
	v_mov_b64_e32 v[178:179], v[148:149]
	s_and_b64 vcc, exec, s[10:11]
	s_mov_b32 s0, s4
	v_lshl_add_u64 v[114:115], v[106:107], 0, v[142:143]
	v_cvt_pk_bf16_f32 v106, v118, v119
	v_cvt_pk_bf16_f32 v107, v120, v121
	v_cvt_pk_bf16_f32 v108, v110, v111
	v_cvt_pk_bf16_f32 v109, v112, v113
	ds_bpermute_b32 v168, v254, v106
	ds_bpermute_b32 v169, v254, v107
	ds_bpermute_b32 v170, v254, v108
	ds_bpermute_b32 v171, v254, v109
	v_mov_b64_e32 v[180:181], v[114:115]
	s_waitcnt lgkmcnt(8)
	global_store_dwordx4 v[176:177], v[160:163], off
	v_cvt_pk_bf16_f32 v98, v98, v99
	v_cvt_pk_bf16_f32 v99, v100, v101
	v_cvt_pk_bf16_f32 v100, v90, v91
	v_or_b32_e32 v90, 32, v150
	v_mad_i64_i32 v[90:91], s[28:29], v90, s46, v[140:141]
	v_cvt_pk_bf16_f32 v101, v92, v93
	ds_bpermute_b32 v172, v254, v98
	ds_bpermute_b32 v173, v254, v99
	ds_bpermute_b32 v174, v254, v100
	ds_bpermute_b32 v175, v254, v101
	v_mov_b64_e32 v[182:183], v[114:115]
	s_waitcnt lgkmcnt(8)
	global_store_dwordx4 v[178:179], v[164:167], off offset:256
	s_mov_b32 s2, s6
	s_mov_b64 s[30:31], s[12:13]
	v_lshl_add_u64 v[98:99], v[90:91], 0, v[142:143]
	v_cvt_pk_bf16_f32 v90, v102, v103
	v_cvt_pk_bf16_f32 v91, v104, v105
	v_cvt_pk_bf16_f32 v92, v94, v95
	v_cvt_pk_bf16_f32 v93, v96, v97
	ds_bpermute_b32 v160, v254, v90
	ds_bpermute_b32 v161, v254, v91
	ds_bpermute_b32 v162, v254, v92
	ds_bpermute_b32 v163, v254, v93
	v_mov_b64_e32 v[176:177], v[98:99]
	s_waitcnt lgkmcnt(8)
; DEVI unsigned cvt_pk_bf16(float lo, float hi) { unsigned r; asm volatile("v_cvt_pk_bf16_f32 %0, %1, %2" : "=v"(r) : "v"(lo), "v"(hi)); return r; }
; #define PG8_WAIT_V(n) asm volatile("s_waitcnt vmcnt(" #n ")" ::: "memory")
; #define PG8_BAR __builtin_amdgcn_s_barrier()
;     DEVI void operator()(f32x4 (&acc)[2][2][4][2], const Unit& u, int wr, int wc, int fr, int fq) const {
;     ...
;             for (int m = 0; m < 4; ++m) { bf16_t* rowp = O + (size_t)(row0 + ai * HALF + m * 16) * ldc + col0;
;                 float rstd = 1.0f; if (RS) rstd = rsqrtf(ssq[row0 + ai * HALF + m * 16] * (1.0f / 1024.0f) + EPS);
; #pragma unroll
;                 for (int bj = 0; bj < 2; ++bj) { f32x4 v0 = acc[ai][bj][m][0], v1 = acc[ai][bj][m][1];
;                     if (RS) { v0 = v0 * rstd + sh[bj][0]; v1 = v1 * rstd + sh[bj][1]; }
;                     if (ACT == 1) {
; #pragma unroll
;                         for (int j = 0; j < 4; ++j) { const float a = fmaxf(v0[j], 0.f), b = fmaxf(v1[j], 0.f); v0[j] = a * a; v1[j] = b * b; } }
;                     if (ACT == 2) {
; #pragma unroll
;                         for (int j = 0; j < 4; ++j) { v0[j] = 1.0f + __expf(-fminf(fmaxf(v0[j], -30.f), 30.f)); v1[j] = 1.0f + __expf(-fminf(fmaxf(v1[j], -30.f), 30.f)); } }
;                     u32x4 w; w.x = cvt_pk_bf16(v0[0], v0[1]); w.y = cvt_pk_bf16(v0[2], v0[3]); w.z = cvt_pk_bf16(v1[0], v1[1]); w.w = cvt_pk_bf16(v1[2], v1[3]);
;                     *(u32x4*)(rowp + bj * HALF) = w; } }
; template <class Epi>
; DEVI void gemm_phase(const int wv, LAS unsigned char* lds, const Gemm g, const Order& S, const Epi& E) {
;     ...
;         if (!has_next) break;
;         cur = nxt; cA = nA; cB = nB; ++ui;
;     }
;     PG8_WAIT_V(0);
;     if (wr == 0) PG8_BAR;
;     PG8_BAR;
	global_store_dwordx4 v[180:181], v[168:171], off
	v_cvt_pk_bf16_f32 v82, v82, v83
	v_cvt_pk_bf16_f32 v83, v84, v85
	v_cvt_pk_bf16_f32 v84, v74, v75
	v_or_b32_e32 v74, 48, v150
	v_mad_i64_i32 v[74:75], s[28:29], v74, s46, v[140:141]
	v_cvt_pk_bf16_f32 v85, v76, v77
	ds_bpermute_b32 v164, v254, v82
	ds_bpermute_b32 v165, v254, v83
	ds_bpermute_b32 v166, v254, v84
	ds_bpermute_b32 v167, v254, v85
	v_mov_b64_e32 v[178:179], v[98:99]
	s_waitcnt lgkmcnt(8)
	global_store_dwordx4 v[182:183], v[172:175], off offset:256
	s_nop 1
	v_lshl_add_u64 v[82:83], v[74:75], 0, v[142:143]
	v_cvt_pk_bf16_f32 v74, v86, v87
	v_cvt_pk_bf16_f32 v75, v88, v89
	v_cvt_pk_bf16_f32 v76, v78, v79
	v_cvt_pk_bf16_f32 v77, v80, v81
	ds_bpermute_b32 v168, v254, v74
	ds_bpermute_b32 v169, v254, v75
	ds_bpermute_b32 v170, v254, v76
	ds_bpermute_b32 v171, v254, v77
	v_mov_b64_e32 v[180:181], v[82:83]
	s_waitcnt lgkmcnt(8)
	global_store_dwordx4 v[176:177], v[160:163], off
	v_cvt_pk_bf16_f32 v70, v70, v71
	v_cvt_pk_bf16_f32 v71, v72, v73
	v_cvt_pk_bf16_f32 v72, v66, v67
	v_add_u32_e32 v66, 0x80, v150
	v_mad_i64_i32 v[66:67], s[28:29], v66, s46, v[140:141]
	v_lshl_add_u64 v[66:67], v[66:67], 0, v[142:143]
	v_cvt_pk_bf16_f32 v73, v68, v69
	ds_bpermute_b32 v172, v254, v70
	ds_bpermute_b32 v173, v254, v71
	ds_bpermute_b32 v174, v254, v72
	ds_bpermute_b32 v175, v254, v73
	v_mov_b64_e32 v[182:183], v[82:83]
	s_waitcnt lgkmcnt(8)
	global_store_dwordx4 v[178:179], v[164:167], off offset:256
	v_cvt_pk_bf16_f32 v62, v62, v63
	v_cvt_pk_bf16_f32 v63, v64, v65
	v_cvt_pk_bf16_f32 v64, v58, v59
	v_cvt_pk_bf16_f32 v65, v60, v61
	ds_bpermute_b32 v160, v254, v62
	ds_bpermute_b32 v161, v254, v63
	ds_bpermute_b32 v162, v254, v64
	ds_bpermute_b32 v163, v254, v65
	v_mov_b64_e32 v[176:177], v[66:67]
	s_waitcnt lgkmcnt(8)
	global_store_dwordx4 v[180:181], v[168:171], off
	v_cvt_pk_bf16_f32 v50, v50, v51
	v_cvt_pk_bf16_f32 v51, v52, v53
	v_cvt_pk_bf16_f32 v52, v42, v43
	v_add_u32_e32 v42, 0x90, v150
	v_mad_i64_i32 v[42:43], s[28:29], v42, s46, v[140:141]
	v_cvt_pk_bf16_f32 v53, v44, v45
	ds_bpermute_b32 v164, v254, v50
	ds_bpermute_b32 v165, v254, v51
	ds_bpermute_b32 v166, v254, v52
	ds_bpermute_b32 v167, v254, v53
	v_mov_b64_e32 v[178:179], v[66:67]
	s_waitcnt lgkmcnt(8)
	global_store_dwordx4 v[182:183], v[172:175], off offset:256
	s_nop 1
	v_lshl_add_u64 v[50:51], v[42:43], 0, v[142:143]
	v_cvt_pk_bf16_f32 v42, v54, v55
	v_cvt_pk_bf16_f32 v43, v56, v57
	v_cvt_pk_bf16_f32 v44, v46, v47
	v_cvt_pk_bf16_f32 v45, v48, v49
	ds_bpermute_b32 v168, v254, v42
	ds_bpermute_b32 v169, v254, v43
	ds_bpermute_b32 v170, v254, v44
	ds_bpermute_b32 v171, v254, v45
	v_mov_b64_e32 v[180:181], v[50:51]
	s_waitcnt lgkmcnt(8)
	global_store_dwordx4 v[176:177], v[160:163], off
	v_cvt_pk_bf16_f32 v34, v34, v35
	v_cvt_pk_bf16_f32 v35, v36, v37
	v_cvt_pk_bf16_f32 v36, v26, v27
	v_add_u32_e32 v26, 0xa0, v150
	v_mad_i64_i32 v[26:27], s[28:29], v26, s46, v[140:141]
	v_cvt_pk_bf16_f32 v37, v28, v29
	ds_bpermute_b32 v172, v254, v34
	ds_bpermute_b32 v173, v254, v35
	ds_bpermute_b32 v174, v254, v36
	ds_bpermute_b32 v175, v254, v37
	v_mov_b64_e32 v[182:183], v[50:51]
	s_waitcnt lgkmcnt(8)
	global_store_dwordx4 v[178:179], v[164:167], off offset:256
	s_nop 1
	v_lshl_add_u64 v[34:35], v[26:27], 0, v[142:143]
	v_cvt_pk_bf16_f32 v26, v38, v39
	v_cvt_pk_bf16_f32 v27, v40, v41
	v_cvt_pk_bf16_f32 v28, v30, v31
	v_cvt_pk_bf16_f32 v29, v32, v33
	ds_bpermute_b32 v160, v254, v26
	ds_bpermute_b32 v161, v254, v27
	ds_bpermute_b32 v162, v254, v28
	ds_bpermute_b32 v163, v254, v29
	v_mov_b64_e32 v[176:177], v[34:35]
	s_waitcnt lgkmcnt(8)
	global_store_dwordx4 v[180:181], v[168:171], off
	v_cvt_pk_bf16_f32 v18, v18, v19
	v_cvt_pk_bf16_f32 v19, v20, v21
	v_cvt_pk_bf16_f32 v20, v10, v11
	v_add_u32_e32 v10, 0xb0, v150
	v_mad_i64_i32 v[10:11], s[28:29], v10, s46, v[140:141]
	v_cvt_pk_bf16_f32 v21, v12, v13
	ds_bpermute_b32 v164, v254, v18
	ds_bpermute_b32 v165, v254, v19
	ds_bpermute_b32 v166, v254, v20
	ds_bpermute_b32 v167, v254, v21
	v_mov_b64_e32 v[178:179], v[34:35]
	s_waitcnt lgkmcnt(8)
	global_store_dwordx4 v[182:183], v[172:175], off offset:256
	s_mov_b64 s[28:29], s[8:9]
	s_nop 0
	v_lshl_add_u64 v[18:19], v[10:11], 0, v[142:143]
	v_cvt_pk_bf16_f32 v10, v22, v23
	v_cvt_pk_bf16_f32 v11, v24, v25
	v_cvt_pk_bf16_f32 v12, v14, v15
	v_cvt_pk_bf16_f32 v13, v16, v17
	ds_bpermute_b32 v168, v254, v10
	ds_bpermute_b32 v169, v254, v11
	ds_bpermute_b32 v170, v254, v12
	ds_bpermute_b32 v171, v254, v13
	v_mov_b64_e32 v[180:181], v[18:19]
	s_waitcnt lgkmcnt(8)
	global_store_dwordx4 v[176:177], v[160:163], off
	v_cvt_pk_bf16_f32 v6, v6, v7
	v_cvt_pk_bf16_f32 v7, v8, v9
	v_cvt_pk_bf16_f32 v8, v2, v3
	v_cvt_pk_bf16_f32 v9, v4, v5
	ds_bpermute_b32 v172, v254, v6
	ds_bpermute_b32 v173, v254, v7
	ds_bpermute_b32 v174, v254, v8
	ds_bpermute_b32 v175, v254, v9
	v_mov_b64_e32 v[182:183], v[18:19]
	s_waitcnt lgkmcnt(8)
	global_store_dwordx4 v[178:179], v[164:167], off offset:256
	s_waitcnt lgkmcnt(4)
	global_store_dwordx4 v[180:181], v[168:171], off
	s_waitcnt lgkmcnt(0)
	global_store_dwordx4 v[182:183], v[172:175], off offset:256
	s_cbranch_vccz .LBB0_281
	v_readlane_b32 s0, v252, 13
	s_waitcnt vmcnt(0)
	v_readlane_b32 s1, v252, 14
	s_andn2_b64 vcc, exec, s[0:1]
	s_movk_i32 s55, 0xc00
	s_cbranch_vccnz .LBB0_291
	s_barrier

; #define PG8_STAGE(bufoff, gbase, voff) do { _Pragma("unroll") for (int _i = 0; _i < 2; ++_i) \
;         __builtin_amdgcn_global_load_lds((const unsigned*)((const char*)(gbase) + (voff)[_i]), (LAS unsigned*)(lds + (bufoff) + ldsw + _i * 8192), 16, 0, 0); } while (0)
; #define PG8_LDA(dst, b, h) do { _Pragma("unroll") for (int m = 0; m < 4; ++m) _Pragma("unroll") for (int k = 0; k < 2; ++k) dst[m][k] = *(const LAS bf16x8*)(lds + PG8_SA(b, h) + aoff + m * 2048 + k * 1024); } while (0)
; #define PG8_LDB(dst, b, h) do { _Pragma("unroll") for (int n = 0; n < 2; ++n) _Pragma("unroll") for (int k = 0; k < 2; ++k) dst[n][k] = *(const LAS bf16x8*)(lds + PG8_SB(b, h) + boff + n * 2048 + k * 1024); } while (0)
; #define PG8_MMA(ai, bj, At, Bt) do { __builtin_amdgcn_s_setprio(1); _Pragma("unroll") for (int m = 0; m < 4; ++m) _Pragma("unroll") for (int n = 0; n < 2; ++n) _Pragma("unroll") for (int k = 0; k < 2; ++k) \
;         acc[ai][bj][m][n] = __builtin_amdgcn_mfma_f32_16x16x32_bf16(Bt[n][k], At[m][k], acc[ai][bj][m][n], 0, 0, 0); __builtin_amdgcn_s_setprio(0); } while (0)
; #define PG8_WAIT_V(n) asm volatile("s_waitcnt vmcnt(" #n ")" ::: "memory")
; #define PG8_WAIT_L(n) asm volatile("s_waitcnt lgkmcnt(" #n ")" ::: "memory")
; #define PG8_BAR __builtin_amdgcn_s_barrier()
; #define PG8_SCHED __builtin_amdgcn_sched_barrier(0)
; template <class Epi>
; DEVI void gemm_phase(const int wv, LAS unsigned char* lds, const Gemm g, const Order& S, const Epi& E) {
;     ...
;             PG8_LDB(B0, 0, 0); PG8_SCHED; PG8_LDA(At, 0, 0); PG8_STAGE(PG8_SA(1, 1), a1 + hstepA, voffA);
;             PG8_WAIT_L(8); PG8_BAR; PG8_WAIT_L(0); PG8_MMA(0, 0, At, B0); PG8_BAR; PG8_SCHED;
;             PG8_LDB(B1, 0, 1); PG8_STAGE(PG8_SB(0, 0), b2, voffB);
;             PG8_BAR; PG8_WAIT_L(0); PG8_MMA(0, 1, At, B1); PG8_BAR;
;             PG8_LDA(At, 0, 1); PG8_STAGE(PG8_SA(0, 0), a2, voffA);
;             PG8_BAR; PG8_WAIT_L(0); PG8_MMA(1, 0, At, B0); PG8_BAR; PG8_SCHED;
;             PG8_STAGE(PG8_SB(0, 1), b2 + hstepB, voffB);
;             PG8_WAIT_V(6); PG8_BAR; PG8_MMA(1, 1, At, B1); PG8_BAR;
.LBB0_814:
	s_add_u32 s30, s28, 0xfffc0080
	s_addc_u32 s31, s29, -1
	s_add_i32 s58, 0, 0x10000
	v_add_u32_e32 v156, s58, v145
	ds_read_b128 v[140:143], v156
	ds_read_b128 v[148:151], v156 offset:1024
	ds_read_b128 v[152:155], v156 offset:2048
	ds_read_b128 v[156:159], v156 offset:3072
	s_cmp_eq_u32 s57, 12
	s_cselect_b32 s37, s3, s31
	s_cselect_b32 s36, s53, s30
	s_cselect_b32 s31, s1, s56
	s_cselect_b32 s30, s54, s55
	v_lshl_add_u64 v[192:193], s[28:29], 0, v[136:137]
	s_add_i32 m0, s11, 0xc000
	ds_read_b128 v[160:163], v147
	ds_read_b128 v[164:167], v147 offset:1024
	ds_read_b128 v[168:171], v147 offset:2048
	ds_read_b128 v[172:175], v147 offset:3072
	ds_read_b128 v[176:179], v147 offset:4096
	ds_read_b128 v[180:183], v147 offset:5120
	ds_read_b128 v[184:187], v147 offset:6144
	ds_read_b128 v[188:191], v147 offset:7168
	global_load_lds_dwordx4 v[192:193], off
	v_lshl_add_u64 v[192:193], s[28:29], 0, v[138:139]
	s_add_i32 m0, s11, 0xe000
	s_nop 0
	global_load_lds_dwordx4 v[192:193], off
	s_waitcnt lgkmcnt(8)
	s_barrier
	s_waitcnt lgkmcnt(0)
	s_setprio 1
	s_waitcnt lgkmcnt(0)
	v_mfma_f32_16x16x32_bf16 v[126:129], v[140:143], v[160:163], v[126:129]
	v_mfma_f32_16x16x32_bf16 v[122:125], v[152:155], v[160:163], v[122:125]
	v_mfma_f32_16x16x32_bf16 v[110:113], v[140:143], v[168:171], v[110:113]
	v_mfma_f32_16x16x32_bf16 v[106:109], v[152:155], v[168:171], v[106:109]
	v_mfma_f32_16x16x32_bf16 v[94:97], v[140:143], v[176:179], v[94:97]
	v_mfma_f32_16x16x32_bf16 v[90:93], v[152:155], v[176:179], v[90:93]
	v_mfma_f32_16x16x32_bf16 v[78:81], v[140:143], v[184:187], v[78:81]
	v_mfma_f32_16x16x32_bf16 v[74:77], v[152:155], v[184:187], v[74:77]
	v_mfma_f32_16x16x32_bf16 v[126:129], v[148:151], v[164:167], v[126:129]
	v_mfma_f32_16x16x32_bf16 v[122:125], v[156:159], v[164:167], v[122:125]
	v_mfma_f32_16x16x32_bf16 v[110:113], v[148:151], v[172:175], v[110:113]
	v_mfma_f32_16x16x32_bf16 v[106:109], v[156:159], v[172:175], v[106:109]
	v_mfma_f32_16x16x32_bf16 v[94:97], v[148:151], v[180:183], v[94:97]
	v_mfma_f32_16x16x32_bf16 v[90:93], v[156:159], v[180:183], v[90:93]
	v_mfma_f32_16x16x32_bf16 v[78:81], v[148:151], v[188:191], v[78:81]
	v_mfma_f32_16x16x32_bf16 v[74:77], v[156:159], v[188:191], v[74:77]
	s_setprio 0
	s_barrier
	s_add_i32 s60, 0, 0x14000
	s_add_i32 s58, s58, s95
	v_add_u32_e32 v199, s60, v145
	v_lshl_add_u64 v[212:213], s[30:31], 0, v[0:1]
	s_mov_b32 m0, s58
	ds_read_b128 v[192:195], v199
	ds_read_b128 v[200:203], v199 offset:1024
	ds_read_b128 v[204:207], v199 offset:2048
	ds_read_b128 v[208:211], v199 offset:3072
	global_load_lds_dwordx4 v[212:213], off
	v_lshl_add_u64 v[214:215], s[30:31], 0, v[130:131]
	s_add_i32 m0, s58, 0x2000
	s_nop 0
	global_load_lds_dwordx4 v[214:215], off
	s_barrier
	s_waitcnt lgkmcnt(0)
	s_setprio 1
	s_waitcnt lgkmcnt(0)
	v_mfma_f32_16x16x32_bf16 v[118:121], v[192:195], v[160:163], v[118:121]
	v_mfma_f32_16x16x32_bf16 v[114:117], v[204:207], v[160:163], v[114:117]
	v_mfma_f32_16x16x32_bf16 v[102:105], v[192:195], v[168:171], v[102:105]
	v_mfma_f32_16x16x32_bf16 v[98:101], v[204:207], v[168:171], v[98:101]
	v_mfma_f32_16x16x32_bf16 v[86:89], v[192:195], v[176:179], v[86:89]
	v_mfma_f32_16x16x32_bf16 v[82:85], v[204:207], v[176:179], v[82:85]
	v_mfma_f32_16x16x32_bf16 v[70:73], v[192:195], v[184:187], v[70:73]
	v_mfma_f32_16x16x32_bf16 v[66:69], v[204:207], v[184:187], v[66:69]
	v_mfma_f32_16x16x32_bf16 v[118:121], v[200:203], v[164:167], v[118:121]
	v_mfma_f32_16x16x32_bf16 v[114:117], v[208:211], v[164:167], v[114:117]
	v_mfma_f32_16x16x32_bf16 v[102:105], v[200:203], v[172:175], v[102:105]
	v_mfma_f32_16x16x32_bf16 v[98:101], v[208:211], v[172:175], v[98:101]
	v_mfma_f32_16x16x32_bf16 v[86:89], v[200:203], v[180:183], v[86:89]
	v_mfma_f32_16x16x32_bf16 v[82:85], v[208:211], v[180:183], v[82:85]
	v_mfma_f32_16x16x32_bf16 v[70:73], v[200:203], v[188:191], v[70:73]
	v_mfma_f32_16x16x32_bf16 v[66:69], v[208:211], v[188:191], v[66:69]
	s_setprio 0
	s_mov_b32 m0, s11
	v_lshl_add_u64 v[216:217], s[36:37], 0, v[134:135]
	s_barrier
	ds_read_b128 v[160:163], v147 offset:16384
	ds_read_b128 v[164:167], v147 offset:17408
	ds_read_b128 v[168:171], v147 offset:18432
	ds_read_b128 v[172:175], v147 offset:19456
	ds_read_b128 v[176:179], v147 offset:20480
	ds_read_b128 v[180:183], v147 offset:21504
	ds_read_b128 v[184:187], v147 offset:22528
	ds_read_b128 v[188:191], v147 offset:23552
	global_load_lds_dwordx4 v[216:217], off
	v_lshl_add_u64 v[218:219], s[36:37], 0, v[132:133]
	s_mov_b32 m0, s13
	s_nop 0
	global_load_lds_dwordx4 v[218:219], off
	s_barrier
	s_waitcnt lgkmcnt(0)
	s_setprio 1
	s_waitcnt lgkmcnt(0)
	v_mfma_f32_16x16x32_bf16 v[62:65], v[140:143], v[160:163], v[62:65]
	v_mfma_f32_16x16x32_bf16 v[58:61], v[152:155], v[160:163], v[58:61]
	v_mfma_f32_16x16x32_bf16 v[46:49], v[140:143], v[168:171], v[46:49]
	v_mfma_f32_16x16x32_bf16 v[42:45], v[152:155], v[168:171], v[42:45]
	v_mfma_f32_16x16x32_bf16 v[30:33], v[140:143], v[176:179], v[30:33]
	v_mfma_f32_16x16x32_bf16 v[26:29], v[152:155], v[176:179], v[26:29]
	v_mfma_f32_16x16x32_bf16 v[14:17], v[140:143], v[184:187], v[14:17]
	v_mfma_f32_16x16x32_bf16 v[10:13], v[152:155], v[184:187], v[10:13]
	v_mfma_f32_16x16x32_bf16 v[62:65], v[148:151], v[164:167], v[62:65]
	v_mfma_f32_16x16x32_bf16 v[58:61], v[156:159], v[164:167], v[58:61]
	v_mfma_f32_16x16x32_bf16 v[46:49], v[148:151], v[172:175], v[46:49]
	v_mfma_f32_16x16x32_bf16 v[42:45], v[156:159], v[172:175], v[42:45]
	v_mfma_f32_16x16x32_bf16 v[30:33], v[148:151], v[180:183], v[30:33]
	v_mfma_f32_16x16x32_bf16 v[26:29], v[156:159], v[180:183], v[26:29]
	v_mfma_f32_16x16x32_bf16 v[14:17], v[148:151], v[188:191], v[14:17]
	v_mfma_f32_16x16x32_bf16 v[10:13], v[156:159], v[188:191], v[10:13]
	s_setprio 0
	s_barrier
; #define PG8_STAGE(bufoff, gbase, voff) do { _Pragma("unroll") for (int _i = 0; _i < 2; ++_i) \
;         __builtin_amdgcn_global_load_lds((const unsigned*)((const char*)(gbase) + (voff)[_i]), (LAS unsigned*)(lds + (bufoff) + ldsw + _i * 8192), 16, 0, 0); } while (0)
; #define PG8_LDA(dst, b, h) do { _Pragma("unroll") for (int m = 0; m < 4; ++m) _Pragma("unroll") for (int k = 0; k < 2; ++k) dst[m][k] = *(const LAS bf16x8*)(lds + PG8_SA(b, h) + aoff + m * 2048 + k * 1024); } while (0)
; #define PG8_LDB(dst, b, h) do { _Pragma("unroll") for (int n = 0; n < 2; ++n) _Pragma("unroll") for (int k = 0; k < 2; ++k) dst[n][k] = *(const LAS bf16x8*)(lds + PG8_SB(b, h) + boff + n * 2048 + k * 1024); } while (0)
; #define PG8_MMA(ai, bj, At, Bt) do { __builtin_amdgcn_s_setprio(1); _Pragma("unroll") for (int m = 0; m < 4; ++m) _Pragma("unroll") for (int n = 0; n < 2; ++n) _Pragma("unroll") for (int k = 0; k < 2; ++k) \
;         acc[ai][bj][m][n] = __builtin_amdgcn_mfma_f32_16x16x32_bf16(Bt[n][k], At[m][k], acc[ai][bj][m][n], 0, 0, 0); __builtin_amdgcn_s_setprio(0); } while (0)
; #define PG8_WAIT_V(n) asm volatile("s_waitcnt vmcnt(" #n ")" ::: "memory")
; #define PG8_WAIT_L(n) asm volatile("s_waitcnt lgkmcnt(" #n ")" ::: "memory")
; #define PG8_BAR __builtin_amdgcn_s_barrier()
; #define PG8_SCHED __builtin_amdgcn_sched_barrier(0)
; template <class Epi>
; DEVI void gemm_phase(const int wv, LAS unsigned char* lds, const Gemm g, const Order& S, const Epi& E) {
;     ...
;             PG8_WAIT_V(6); PG8_BAR; PG8_MMA(1, 1, At, B1); PG8_BAR;
;             PG8_LDB(B0, 1, 0); PG8_SCHED; PG8_LDA(At, 1, 0); PG8_STAGE(PG8_SA(0, 1), a2 + hstepA, voffA);
;             PG8_WAIT_L(8); PG8_BAR; PG8_WAIT_L(0); PG8_MMA(0, 0, At, B0); PG8_BAR; PG8_SCHED;
;             PG8_LDB(B1, 1, 1); PG8_STAGE(PG8_SB(1, 0), b3, voffB);
;             PG8_BAR; PG8_WAIT_L(0); PG8_MMA(0, 1, At, B1); PG8_BAR;
;             PG8_LDA(At, 1, 1); PG8_STAGE(PG8_SA(1, 0), a3, voffA);
;             PG8_BAR; PG8_WAIT_L(0); PG8_MMA(1, 0, At, B0); PG8_BAR; PG8_SCHED;
	s_add_u32 s58, s30, 0x40000
	s_addc_u32 s59, s31, 0
	s_add_i32 s60, s60, s95
	v_lshl_add_u64 v[140:141], s[58:59], 0, v[0:1]
	s_mov_b32 m0, s60
	s_nop 0
	global_load_lds_dwordx4 v[140:141], off
	v_lshl_add_u64 v[140:141], s[58:59], 0, v[130:131]
	s_add_i32 m0, s60, 0x2000
	s_nop 0
	global_load_lds_dwordx4 v[140:141], off
	s_waitcnt vmcnt(6)
	s_barrier
	s_setprio 1
	v_mfma_f32_16x16x32_bf16 v[54:57], v[192:195], v[160:163], v[54:57]
	v_mfma_f32_16x16x32_bf16 v[50:53], v[204:207], v[160:163], v[50:53]
	v_mfma_f32_16x16x32_bf16 v[38:41], v[192:195], v[168:171], v[38:41]
	v_mfma_f32_16x16x32_bf16 v[34:37], v[204:207], v[168:171], v[34:37]
	v_mfma_f32_16x16x32_bf16 v[22:25], v[192:195], v[176:179], v[22:25]
	v_mfma_f32_16x16x32_bf16 v[18:21], v[204:207], v[176:179], v[18:21]
	v_mfma_f32_16x16x32_bf16 v[6:9], v[192:195], v[184:187], v[6:9]
	v_mfma_f32_16x16x32_bf16 v[2:5], v[204:207], v[184:187], v[2:5]
	v_mfma_f32_16x16x32_bf16 v[54:57], v[200:203], v[164:167], v[54:57]
	v_mfma_f32_16x16x32_bf16 v[50:53], v[208:211], v[164:167], v[50:53]
	v_mfma_f32_16x16x32_bf16 v[38:41], v[200:203], v[172:175], v[38:41]
	v_mfma_f32_16x16x32_bf16 v[34:37], v[208:211], v[172:175], v[34:37]
	v_mfma_f32_16x16x32_bf16 v[22:25], v[200:203], v[180:183], v[22:25]
	v_mfma_f32_16x16x32_bf16 v[18:21], v[208:211], v[180:183], v[18:21]
	v_mfma_f32_16x16x32_bf16 v[6:9], v[200:203], v[188:191], v[6:9]
	v_mfma_f32_16x16x32_bf16 v[2:5], v[208:211], v[188:191], v[2:5]
	s_setprio 0
	s_add_i32 s58, 0, 0x18000
	v_add_u32_e32 v156, s58, v145
	s_barrier
	ds_read_b128 v[140:143], v156
	ds_read_b128 v[148:151], v156 offset:1024
	ds_read_b128 v[152:155], v156 offset:2048
	ds_read_b128 v[156:159], v156 offset:3072
	s_add_u32 s36, s36, 0x40000
	s_addc_u32 s37, s37, 0
	s_mov_b32 m0, s40
	v_lshl_add_u64 v[192:193], s[36:37], 0, v[134:135]
	ds_read_b128 v[160:163], v147 offset:32768
	ds_read_b128 v[164:167], v147 offset:33792
	ds_read_b128 v[168:171], v147 offset:34816
	ds_read_b128 v[172:175], v147 offset:35840
	ds_read_b128 v[176:179], v147 offset:36864
	ds_read_b128 v[180:183], v147 offset:37888
	ds_read_b128 v[184:187], v147 offset:38912
	ds_read_b128 v[188:191], v147 offset:39936
	global_load_lds_dwordx4 v[192:193], off
	v_lshl_add_u64 v[192:193], s[36:37], 0, v[132:133]
	s_mov_b32 m0, s41
	s_nop 0
	global_load_lds_dwordx4 v[192:193], off
	s_waitcnt lgkmcnt(8)
	s_barrier
	s_waitcnt lgkmcnt(0)
	s_setprio 1
	s_waitcnt lgkmcnt(0)
	v_mfma_f32_16x16x32_bf16 v[126:129], v[140:143], v[160:163], v[126:129]
	v_mfma_f32_16x16x32_bf16 v[122:125], v[152:155], v[160:163], v[122:125]
	v_mfma_f32_16x16x32_bf16 v[110:113], v[140:143], v[168:171], v[110:113]
	v_mfma_f32_16x16x32_bf16 v[106:109], v[152:155], v[168:171], v[106:109]
	v_mfma_f32_16x16x32_bf16 v[94:97], v[140:143], v[176:179], v[94:97]
	v_mfma_f32_16x16x32_bf16 v[90:93], v[152:155], v[176:179], v[90:93]
	v_mfma_f32_16x16x32_bf16 v[78:81], v[140:143], v[184:187], v[78:81]
	v_mfma_f32_16x16x32_bf16 v[74:77], v[152:155], v[184:187], v[74:77]
	v_mfma_f32_16x16x32_bf16 v[126:129], v[148:151], v[164:167], v[126:129]
	v_mfma_f32_16x16x32_bf16 v[122:125], v[156:159], v[164:167], v[122:125]
	v_mfma_f32_16x16x32_bf16 v[110:113], v[148:151], v[172:175], v[110:113]
	v_mfma_f32_16x16x32_bf16 v[106:109], v[156:159], v[172:175], v[106:109]
	v_mfma_f32_16x16x32_bf16 v[94:97], v[148:151], v[180:183], v[94:97]
	v_mfma_f32_16x16x32_bf16 v[90:93], v[156:159], v[180:183], v[90:93]
	v_mfma_f32_16x16x32_bf16 v[78:81], v[148:151], v[188:191], v[78:81]
	v_mfma_f32_16x16x32_bf16 v[74:77], v[156:159], v[188:191], v[74:77]
	s_setprio 0
	s_barrier
	s_add_i32 s36, 0, 0x1c000
	s_add_i32 s37, s58, s95
	v_add_u32_e32 v199, s36, v145
	v_lshl_add_u64 v[212:213], v[212:213], 0, s[92:93]
	s_mov_b32 m0, s37
	ds_read_b128 v[192:195], v199
	ds_read_b128 v[200:203], v199 offset:1024
	ds_read_b128 v[204:207], v199 offset:2048
	ds_read_b128 v[208:211], v199 offset:3072
	global_load_lds_dwordx4 v[212:213], off
	v_lshl_add_u64 v[212:213], v[214:215], 0, s[92:93]
	s_add_i32 m0, s37, 0x2000
	s_nop 0
	global_load_lds_dwordx4 v[212:213], off
	s_barrier
	s_waitcnt lgkmcnt(0)
	s_setprio 1
	s_waitcnt lgkmcnt(0)
	v_mfma_f32_16x16x32_bf16 v[118:121], v[192:195], v[160:163], v[118:121]
	v_mfma_f32_16x16x32_bf16 v[114:117], v[204:207], v[160:163], v[114:117]
	v_mfma_f32_16x16x32_bf16 v[102:105], v[192:195], v[168:171], v[102:105]
	v_mfma_f32_16x16x32_bf16 v[98:101], v[204:207], v[168:171], v[98:101]
	v_mfma_f32_16x16x32_bf16 v[86:89], v[192:195], v[176:179], v[86:89]
	v_mfma_f32_16x16x32_bf16 v[82:85], v[204:207], v[176:179], v[82:85]
	v_mfma_f32_16x16x32_bf16 v[70:73], v[192:195], v[184:187], v[70:73]
	v_mfma_f32_16x16x32_bf16 v[66:69], v[204:207], v[184:187], v[66:69]
	v_mfma_f32_16x16x32_bf16 v[118:121], v[200:203], v[164:167], v[118:121]
	v_mfma_f32_16x16x32_bf16 v[114:117], v[208:211], v[164:167], v[114:117]
	v_mfma_f32_16x16x32_bf16 v[102:105], v[200:203], v[172:175], v[102:105]
	v_mfma_f32_16x16x32_bf16 v[98:101], v[208:211], v[172:175], v[98:101]
	v_mfma_f32_16x16x32_bf16 v[86:89], v[200:203], v[180:183], v[86:89]
	v_mfma_f32_16x16x32_bf16 v[82:85], v[208:211], v[180:183], v[82:85]
	v_mfma_f32_16x16x32_bf16 v[70:73], v[200:203], v[188:191], v[70:73]
	v_mfma_f32_16x16x32_bf16 v[66:69], v[208:211], v[188:191], v[66:69]
	s_setprio 0
	s_mov_b32 m0, s50
	v_lshl_add_u64 v[212:213], v[216:217], 0, s[92:93]
	s_barrier
	ds_read_b128 v[160:163], v147 offset:49152
	ds_read_b128 v[164:167], v147 offset:50176
	ds_read_b128 v[168:171], v147 offset:51200
	ds_read_b128 v[172:175], v147 offset:52224
	ds_read_b128 v[176:179], v147 offset:53248
	ds_read_b128 v[180:183], v147 offset:54272
	ds_read_b128 v[184:187], v147 offset:55296
	ds_read_b128 v[188:191], v147 offset:56320
	global_load_lds_dwordx4 v[212:213], off
	v_lshl_add_u64 v[212:213], v[218:219], 0, s[92:93]
	s_mov_b32 m0, s51
	s_nop 0
	global_load_lds_dwordx4 v[212:213], off
	s_barrier
; DEVI unsigned cvt_pk_bf16(float lo, float hi) { unsigned r; asm volatile("v_cvt_pk_bf16_f32 %0, %1, %2" : "=v"(r) : "v"(lo), "v"(hi)); return r; }
; #define PG8_STAGE(bufoff, gbase, voff) do { _Pragma("unroll") for (int _i = 0; _i < 2; ++_i) \
;         __builtin_amdgcn_global_load_lds((const unsigned*)((const char*)(gbase) + (voff)[_i]), (LAS unsigned*)(lds + (bufoff) + ldsw + _i * 8192), 16, 0, 0); } while (0)
; #define PG8_WAIT_V(n) asm volatile("s_waitcnt vmcnt(" #n ")" ::: "memory")
; #define PG8_WAIT_L(n) asm volatile("s_waitcnt lgkmcnt(" #n ")" ::: "memory")
;     DEVI void operator()(f32x4 (&acc)[2][2][4][2], const Unit& u, int wr, int wc, int fr, int fq) const {
;     ...
;                 for (int bj = 0; bj < 2; ++bj) { f32x4 v0 = acc[ai][bj][m][0], v1 = acc[ai][bj][m][1];
;                     if (RS) { v0 = v0 * rstd + sh[bj][0]; v1 = v1 * rstd + sh[bj][1]; }
;                     if (ACT == 1) {
; #pragma unroll
;                         for (int j = 0; j < 4; ++j) { const float a = fmaxf(v0[j], 0.f), b = fmaxf(v1[j], 0.f); v0[j] = a * a; v1[j] = b * b; } }
;                     if (ACT == 2) {
; #pragma unroll
;                         for (int j = 0; j < 4; ++j) { v0[j] = 1.0f + __expf(-fminf(fmaxf(v0[j], -30.f), 30.f)); v1[j] = 1.0f + __expf(-fminf(fmaxf(v1[j], -30.f), 30.f)); } }
;                     u32x4 w; w.x = cvt_pk_bf16(v0[0], v0[1]); w.y = cvt_pk_bf16(v0[2], v0[3]); w.z = cvt_pk_bf16(v1[0], v1[1]); w.w = cvt_pk_bf16(v1[2], v1[3]);
;                     *(u32x4*)(rowp + bj * HALF) = w; } }
; template <class Epi>
; DEVI void gemm_phase(const int wv, LAS unsigned char* lds, const Gemm g, const Order& S, const Epi& E) {
;     ...
;             PG8_WAIT_V(6); PG8_BAR; PG8_MMA(1, 1, At, B1); PG8_BAR;
;             PG8_LDB(B0, 1, 0); PG8_SCHED; PG8_LDA(At, 1, 0); PG8_STAGE(PG8_SA(0, 1), a2 + hstepA, voffA);
;             PG8_WAIT_L(8); PG8_BAR; PG8_WAIT_L(0); PG8_MMA(0, 0, At, B0); PG8_BAR; PG8_SCHED;
;             PG8_LDB(B1, 1, 1); PG8_STAGE(PG8_SB(1, 0), b3, voffB);
;             PG8_BAR; PG8_WAIT_L(0); PG8_MMA(0, 1, At, B1); PG8_BAR;
;             PG8_LDA(At, 1, 1); PG8_STAGE(PG8_SA(1, 0), a3, voffA);
;             PG8_BAR; PG8_WAIT_L(0); PG8_MMA(1, 0, At, B0); PG8_BAR; PG8_SCHED;
;             PG8_STAGE(PG8_SB(1, 1), b3 + hstepB, voffB);
;             PG8_WAIT_V(6); PG8_BAR; PG8_MMA(1, 1, At, B1); PG8_BAR;
;         }
	s_waitcnt lgkmcnt(0)
	s_setprio 1
	s_waitcnt lgkmcnt(0)
	v_mfma_f32_16x16x32_bf16 v[62:65], v[140:143], v[160:163], v[62:65]
	v_mfma_f32_16x16x32_bf16 v[58:61], v[152:155], v[160:163], v[58:61]
	v_mfma_f32_16x16x32_bf16 v[46:49], v[140:143], v[168:171], v[46:49]
	v_mfma_f32_16x16x32_bf16 v[42:45], v[152:155], v[168:171], v[42:45]
	v_mfma_f32_16x16x32_bf16 v[30:33], v[140:143], v[176:179], v[30:33]
	v_mfma_f32_16x16x32_bf16 v[26:29], v[152:155], v[176:179], v[26:29]
	v_mfma_f32_16x16x32_bf16 v[14:17], v[140:143], v[184:187], v[14:17]
	v_mfma_f32_16x16x32_bf16 v[10:13], v[152:155], v[184:187], v[10:13]
	v_mfma_f32_16x16x32_bf16 v[62:65], v[148:151], v[164:167], v[62:65]
	v_mfma_f32_16x16x32_bf16 v[58:61], v[156:159], v[164:167], v[58:61]
	v_mfma_f32_16x16x32_bf16 v[46:49], v[148:151], v[172:175], v[46:49]
	v_mfma_f32_16x16x32_bf16 v[42:45], v[156:159], v[172:175], v[42:45]
	v_mfma_f32_16x16x32_bf16 v[30:33], v[148:151], v[180:183], v[30:33]
	v_mfma_f32_16x16x32_bf16 v[26:29], v[156:159], v[180:183], v[26:29]
	v_mfma_f32_16x16x32_bf16 v[14:17], v[148:151], v[188:191], v[14:17]
	v_mfma_f32_16x16x32_bf16 v[10:13], v[156:159], v[188:191], v[10:13]
	s_setprio 0
	s_barrier
	s_add_u32 s30, s30, 0x40080
	s_addc_u32 s31, s31, 0
	s_add_i32 s36, s36, s95
	v_lshl_add_u64 v[140:141], s[30:31], 0, v[0:1]
	s_mov_b32 m0, s36
	s_nop 0
	global_load_lds_dwordx4 v[140:141], off
	v_lshl_add_u64 v[140:141], s[30:31], 0, v[130:131]
	s_add_i32 m0, s36, 0x2000
	s_nop 0
	global_load_lds_dwordx4 v[140:141], off
	s_waitcnt vmcnt(6)
	s_barrier
	s_setprio 1
	v_mfma_f32_16x16x32_bf16 v[54:57], v[192:195], v[160:163], v[54:57]
	v_mfma_f32_16x16x32_bf16 v[50:53], v[204:207], v[160:163], v[50:53]
	v_mfma_f32_16x16x32_bf16 v[38:41], v[192:195], v[168:171], v[38:41]
	v_mfma_f32_16x16x32_bf16 v[34:37], v[204:207], v[168:171], v[34:37]
	v_mfma_f32_16x16x32_bf16 v[22:25], v[192:195], v[176:179], v[22:25]
	v_mfma_f32_16x16x32_bf16 v[18:21], v[204:207], v[176:179], v[18:21]
	v_mfma_f32_16x16x32_bf16 v[6:9], v[192:195], v[184:187], v[6:9]
	v_mfma_f32_16x16x32_bf16 v[2:5], v[204:207], v[184:187], v[2:5]
	v_mfma_f32_16x16x32_bf16 v[54:57], v[200:203], v[164:167], v[54:57]
	v_mfma_f32_16x16x32_bf16 v[50:53], v[208:211], v[164:167], v[50:53]
	v_mfma_f32_16x16x32_bf16 v[38:41], v[200:203], v[172:175], v[38:41]
	v_mfma_f32_16x16x32_bf16 v[34:37], v[208:211], v[172:175], v[34:37]
	v_mfma_f32_16x16x32_bf16 v[22:25], v[200:203], v[180:183], v[22:25]
	v_mfma_f32_16x16x32_bf16 v[18:21], v[208:211], v[180:183], v[18:21]
	v_mfma_f32_16x16x32_bf16 v[6:9], v[200:203], v[188:191], v[6:9]
	v_mfma_f32_16x16x32_bf16 v[2:5], v[208:211], v[188:191], v[2:5]
	s_setprio 0
	s_add_i32 s57, s57, 2
	s_add_u32 s28, s28, 0x100
	s_addc_u32 s29, s29, 0
	s_add_u32 s55, s55, 0x100
	s_addc_u32 s56, s56, 0
	s_cmp_gt_u32 s57, 13
	s_barrier
	s_cbranch_scc0 .LBB0_814
	v_max_f32_e32 v122, v122, v122
	v_med3_f32 v122, v122, s49, v238
	v_max_f32_e32 v123, v123, v123
	v_max_f32_e32 v124, v124, v124
	v_mul_f32_e32 v122, 0xbfb8aa3b, v122
	v_med3_f32 v123, v123, s49, v238
	v_med3_f32 v124, v124, s49, v238
	v_exp_f32_e32 v122, v122
	v_mul_f32_e32 v123, 0xbfb8aa3b, v123
	v_mul_f32_e32 v124, 0xbfb8aa3b, v124
	v_exp_f32_e32 v123, v123
	v_exp_f32_e32 v124, v124
	v_add_f32_e32 v149, 1.0, v122
	v_max_f32_e32 v122, v127, v127
	v_max_f32_e32 v126, v126, v126
	v_med3_f32 v122, v122, s49, v238
	v_add_f32_e32 v127, 1.0, v123
	v_max_f32_e32 v123, v128, v128
	v_add_f32_e32 v128, 1.0, v124
	v_max_f32_e32 v124, v129, v129
	v_max_f32_e32 v125, v125, v125
	v_med3_f32 v126, v126, s49, v238
	v_mul_f32_e32 v122, 0xbfb8aa3b, v122
	v_med3_f32 v123, v123, s49, v238
	v_med3_f32 v124, v124, s49, v238
	v_med3_f32 v125, v125, s49, v238
	v_max_f32_e32 v114, v114, v114
	v_max_f32_e32 v115, v115, v115
	v_max_f32_e32 v116, v116, v116
	v_mul_f32_e32 v126, 0xbfb8aa3b, v126
	v_exp_f32_e32 v122, v122
	v_mul_f32_e32 v123, 0xbfb8aa3b, v123
	v_mul_f32_e32 v124, 0xbfb8aa3b, v124
	v_mul_f32_e32 v125, 0xbfb8aa3b, v125
	v_med3_f32 v114, v114, s49, v238
	v_med3_f32 v115, v115, s49, v238
	v_med3_f32 v116, v116, s49, v238
	v_exp_f32_e32 v126, v126
	v_exp_f32_e32 v123, v123
	v_exp_f32_e32 v124, v124
	v_exp_f32_e32 v125, v125
	v_mul_f32_e32 v114, 0xbfb8aa3b, v114
	v_mul_f32_e32 v115, 0xbfb8aa3b, v115
	v_mul_f32_e32 v116, 0xbfb8aa3b, v116
	v_lshl_or_b32 v142, s10, 8, v146
	v_exp_f32_e32 v114, v114
	v_exp_f32_e32 v115, v115
	v_exp_f32_e32 v116, v116
	v_lshl_add_u32 v148, s12, 8, v144
	v_ashrrev_i32_e32 v143, 31, v142
	v_mov_b64_e32 v[140:141], s[24:25]
	s_movk_i32 s1, 0x1800
	v_mad_i64_i32 v[150:151], s[28:29], v148, s1, v[140:141]
	v_lshlrev_b64 v[142:143], 1, v[142:143]
	v_add_f32_e32 v122, 1.0, v122
	v_lshl_add_u64 v[150:151], v[150:151], 0, v[142:143]
	v_add_f32_e32 v126, 1.0, v126
	v_add_f32_e32 v123, 1.0, v123
	v_add_f32_e32 v124, 1.0, v124
	v_add_f32_e32 v125, 1.0, v125
	v_cvt_pk_bf16_f32 v122, v126, v122
	v_cvt_pk_bf16_f32 v123, v123, v124
	v_cvt_pk_bf16_f32 v124, v149, v127
	v_cvt_pk_bf16_f32 v125, v128, v125
	ds_bpermute_b32 v160, v254, v122
	ds_bpermute_b32 v161, v254, v123
	ds_bpermute_b32 v162, v254, v124
	ds_bpermute_b32 v163, v254, v125
	v_mov_b64_e32 v[176:177], v[150:151]
	v_max_f32_e32 v118, v118, v118
	v_max_f32_e32 v117, v117, v117
	v_add_f32_e32 v122, 1.0, v114
	v_max_f32_e32 v114, v119, v119
	v_add_f32_e32 v119, 1.0, v115
	v_max_f32_e32 v115, v120, v120
	v_add_f32_e32 v120, 1.0, v116
	v_max_f32_e32 v116, v121, v121
	v_med3_f32 v114, v114, s49, v238
	v_med3_f32 v115, v115, s49, v238
	v_med3_f32 v116, v116, s49, v238
	v_med3_f32 v118, v118, s49, v238
	v_mul_f32_e32 v114, 0xbfb8aa3b, v114
	v_mul_f32_e32 v115, 0xbfb8aa3b, v115
	v_mul_f32_e32 v116, 0xbfb8aa3b, v116
; DEVI unsigned cvt_pk_bf16(float lo, float hi) { unsigned r; asm volatile("v_cvt_pk_bf16_f32 %0, %1, %2" : "=v"(r) : "v"(lo), "v"(hi)); return r; }
;     DEVI void operator()(f32x4 (&acc)[2][2][4][2], const Unit& u, int wr, int wc, int fr, int fq) const {
;     ...
;                 for (int bj = 0; bj < 2; ++bj) { f32x4 v0 = acc[ai][bj][m][0], v1 = acc[ai][bj][m][1];
;                     if (RS) { v0 = v0 * rstd + sh[bj][0]; v1 = v1 * rstd + sh[bj][1]; }
;                     if (ACT == 1) {
; #pragma unroll
;                         for (int j = 0; j < 4; ++j) { const float a = fmaxf(v0[j], 0.f), b = fmaxf(v1[j], 0.f); v0[j] = a * a; v1[j] = b * b; } }
;                     if (ACT == 2) {
; #pragma unroll
;                         for (int j = 0; j < 4; ++j) { v0[j] = 1.0f + __expf(-fminf(fmaxf(v0[j], -30.f), 30.f)); v1[j] = 1.0f + __expf(-fminf(fmaxf(v1[j], -30.f), 30.f)); } }
;                     u32x4 w; w.x = cvt_pk_bf16(v0[0], v0[1]); w.y = cvt_pk_bf16(v0[2], v0[3]); w.z = cvt_pk_bf16(v1[0], v1[1]); w.w = cvt_pk_bf16(v1[2], v1[3]);
;                     *(u32x4*)(rowp + bj * HALF) = w; } }
	v_med3_f32 v117, v117, s49, v238
	v_max_f32_e32 v106, v106, v106
	v_mul_f32_e32 v118, 0xbfb8aa3b, v118
	v_exp_f32_e32 v114, v114
	v_exp_f32_e32 v115, v115
	v_exp_f32_e32 v116, v116
	v_mul_f32_e32 v117, 0xbfb8aa3b, v117
	v_med3_f32 v106, v106, s49, v238
	v_max_f32_e32 v107, v107, v107
	v_max_f32_e32 v108, v108, v108
	v_exp_f32_e32 v118, v118
	v_exp_f32_e32 v117, v117
	v_mul_f32_e32 v106, 0xbfb8aa3b, v106
	v_med3_f32 v107, v107, s49, v238
	v_med3_f32 v108, v108, s49, v238
	v_exp_f32_e32 v106, v106
	v_mul_f32_e32 v107, 0xbfb8aa3b, v107
	v_mul_f32_e32 v108, 0xbfb8aa3b, v108
	v_exp_f32_e32 v107, v107
	v_exp_f32_e32 v108, v108
	v_add_f32_e32 v114, 1.0, v114
	v_add_f32_e32 v115, 1.0, v115
	v_add_f32_e32 v116, 1.0, v116
	v_add_f32_e32 v118, 1.0, v118
	v_add_f32_e32 v117, 1.0, v117
	v_cvt_pk_bf16_f32 v114, v118, v114
	v_cvt_pk_bf16_f32 v115, v115, v116
	v_cvt_pk_bf16_f32 v116, v122, v119
	v_cvt_pk_bf16_f32 v117, v120, v117
	ds_bpermute_b32 v164, v254, v114
	ds_bpermute_b32 v165, v254, v115
	ds_bpermute_b32 v166, v254, v116
	ds_bpermute_b32 v167, v254, v117
	v_mov_b64_e32 v[178:179], v[150:151]
	v_max_f32_e32 v110, v110, v110
	v_max_f32_e32 v109, v109, v109
	v_add_f32_e32 v116, 1.0, v106
	v_max_f32_e32 v106, v111, v111
	v_med3_f32 v106, v106, s49, v238
	v_add_f32_e32 v111, 1.0, v107
	v_max_f32_e32 v107, v112, v112
	v_add_f32_e32 v112, 1.0, v108
	v_max_f32_e32 v108, v113, v113
	v_med3_f32 v110, v110, s49, v238
	v_mul_f32_e32 v106, 0xbfb8aa3b, v106
	v_med3_f32 v107, v107, s49, v238
	v_med3_f32 v108, v108, s49, v238
	v_med3_f32 v109, v109, s49, v238
	v_max_f32_e32 v98, v98, v98
	v_max_f32_e32 v99, v99, v99
	v_max_f32_e32 v100, v100, v100
	v_mul_f32_e32 v110, 0xbfb8aa3b, v110
	v_exp_f32_e32 v106, v106
	v_mul_f32_e32 v107, 0xbfb8aa3b, v107
	v_mul_f32_e32 v108, 0xbfb8aa3b, v108
	v_mul_f32_e32 v109, 0xbfb8aa3b, v109
	v_med3_f32 v98, v98, s49, v238
	v_med3_f32 v99, v99, s49, v238
	v_med3_f32 v100, v100, s49, v238
	v_exp_f32_e32 v110, v110
	v_exp_f32_e32 v107, v107
	v_exp_f32_e32 v108, v108
	v_exp_f32_e32 v109, v109
	v_mul_f32_e32 v98, 0xbfb8aa3b, v98
	v_mul_f32_e32 v99, 0xbfb8aa3b, v99
	v_mul_f32_e32 v100, 0xbfb8aa3b, v100
	v_exp_f32_e32 v98, v98
	v_exp_f32_e32 v99, v99
	v_exp_f32_e32 v100, v100
	v_or_b32_e32 v114, 16, v148
	v_mad_i64_i32 v[114:115], s[28:29], v114, s1, v[140:141]
	v_add_f32_e32 v106, 1.0, v106
	v_lshl_add_u64 v[114:115], v[114:115], 0, v[142:143]
	v_add_f32_e32 v110, 1.0, v110
	v_add_f32_e32 v107, 1.0, v107
	v_add_f32_e32 v108, 1.0, v108
	v_add_f32_e32 v109, 1.0, v109
	v_cvt_pk_bf16_f32 v106, v110, v106
	v_cvt_pk_bf16_f32 v107, v107, v108
	v_cvt_pk_bf16_f32 v108, v116, v111
	v_cvt_pk_bf16_f32 v109, v112, v109
	ds_bpermute_b32 v168, v254, v106
	ds_bpermute_b32 v169, v254, v107
	ds_bpermute_b32 v170, v254, v108
	ds_bpermute_b32 v171, v254, v109
	v_mov_b64_e32 v[180:181], v[114:115]
	s_waitcnt lgkmcnt(8)
	global_store_dwordx4 v[176:177], v[160:163], off
	v_max_f32_e32 v102, v102, v102
	v_max_f32_e32 v101, v101, v101
	v_add_f32_e32 v106, 1.0, v98
	v_max_f32_e32 v98, v103, v103
	v_add_f32_e32 v103, 1.0, v99
	v_max_f32_e32 v99, v104, v104
	v_add_f32_e32 v104, 1.0, v100
	v_max_f32_e32 v100, v105, v105
	v_med3_f32 v98, v98, s49, v238
	v_med3_f32 v99, v99, s49, v238
	v_med3_f32 v100, v100, s49, v238
	v_med3_f32 v102, v102, s49, v238
	v_mul_f32_e32 v98, 0xbfb8aa3b, v98
	v_mul_f32_e32 v99, 0xbfb8aa3b, v99
	v_mul_f32_e32 v100, 0xbfb8aa3b, v100
	v_med3_f32 v101, v101, s49, v238
	v_max_f32_e32 v90, v90, v90
	v_mul_f32_e32 v102, 0xbfb8aa3b, v102
	v_exp_f32_e32 v98, v98
	v_exp_f32_e32 v99, v99
	v_exp_f32_e32 v100, v100
	v_mul_f32_e32 v101, 0xbfb8aa3b, v101
	v_med3_f32 v90, v90, s49, v238
	v_max_f32_e32 v91, v91, v91
	v_max_f32_e32 v92, v92, v92
	v_exp_f32_e32 v102, v102
	v_exp_f32_e32 v101, v101
	v_mul_f32_e32 v90, 0xbfb8aa3b, v90
	v_med3_f32 v91, v91, s49, v238
	v_med3_f32 v92, v92, s49, v238
	v_exp_f32_e32 v90, v90
	v_mul_f32_e32 v91, 0xbfb8aa3b, v91
	v_mul_f32_e32 v92, 0xbfb8aa3b, v92
	v_exp_f32_e32 v91, v91
	v_exp_f32_e32 v92, v92
	v_add_f32_e32 v98, 1.0, v98
	v_add_f32_e32 v99, 1.0, v99
	v_add_f32_e32 v100, 1.0, v100
	v_add_f32_e32 v102, 1.0, v102
	v_add_f32_e32 v101, 1.0, v101
	v_cvt_pk_bf16_f32 v98, v102, v98
	v_cvt_pk_bf16_f32 v99, v99, v100
	v_cvt_pk_bf16_f32 v100, v106, v103
	v_cvt_pk_bf16_f32 v101, v104, v101
	ds_bpermute_b32 v172, v254, v98
	ds_bpermute_b32 v173, v254, v99
	ds_bpermute_b32 v174, v254, v100
	ds_bpermute_b32 v175, v254, v101
	v_mov_b64_e32 v[182:183], v[114:115]
	s_waitcnt lgkmcnt(8)
	global_store_dwordx4 v[178:179], v[164:167], off offset:256
	v_max_f32_e32 v94, v94, v94
	v_max_f32_e32 v93, v93, v93
	v_add_f32_e32 v100, 1.0, v90
	v_max_f32_e32 v90, v95, v95
	v_med3_f32 v90, v90, s49, v238
	v_add_f32_e32 v95, 1.0, v91
	v_max_f32_e32 v91, v96, v96
	v_add_f32_e32 v96, 1.0, v92
	v_max_f32_e32 v92, v97, v97
	v_med3_f32 v94, v94, s49, v238
	v_mul_f32_e32 v90, 0xbfb8aa3b, v90
	v_med3_f32 v91, v91, s49, v238
	v_med3_f32 v92, v92, s49, v238
	v_med3_f32 v93, v93, s49, v238
	v_max_f32_e32 v82, v82, v82
	v_max_f32_e32 v83, v83, v83
	v_max_f32_e32 v84, v84, v84
	v_mul_f32_e32 v94, 0xbfb8aa3b, v94
	v_exp_f32_e32 v90, v90
	v_mul_f32_e32 v91, 0xbfb8aa3b, v91
	v_mul_f32_e32 v92, 0xbfb8aa3b, v92
	v_mul_f32_e32 v93, 0xbfb8aa3b, v93
	v_med3_f32 v82, v82, s49, v238
	v_med3_f32 v83, v83, s49, v238
	v_med3_f32 v84, v84, s49, v238
	v_exp_f32_e32 v94, v94
	v_exp_f32_e32 v91, v91
	v_exp_f32_e32 v92, v92
	v_exp_f32_e32 v93, v93
	v_mul_f32_e32 v82, 0xbfb8aa3b, v82
	v_mul_f32_e32 v83, 0xbfb8aa3b, v83
	v_mul_f32_e32 v84, 0xbfb8aa3b, v84
	v_exp_f32_e32 v82, v82
	v_exp_f32_e32 v83, v83
	v_exp_f32_e32 v84, v84
	v_or_b32_e32 v98, 32, v148
	v_mad_i64_i32 v[98:99], s[28:29], v98, s1, v[140:141]
	v_add_f32_e32 v90, 1.0, v90
	v_lshl_add_u64 v[98:99], v[98:99], 0, v[142:143]
	v_add_f32_e32 v94, 1.0, v94
	v_add_f32_e32 v91, 1.0, v91
	v_add_f32_e32 v92, 1.0, v92
	v_add_f32_e32 v93, 1.0, v93
	v_cvt_pk_bf16_f32 v90, v94, v90
	v_cvt_pk_bf16_f32 v91, v91, v92
	v_cvt_pk_bf16_f32 v92, v100, v95
	v_cvt_pk_bf16_f32 v93, v96, v93
	ds_bpermute_b32 v160, v254, v90
	ds_bpermute_b32 v161, v254, v91
	ds_bpermute_b32 v162, v254, v92
	ds_bpermute_b32 v163, v254, v93
	v_mov_b64_e32 v[176:177], v[98:99]
	s_waitcnt lgkmcnt(8)
; DEVI unsigned cvt_pk_bf16(float lo, float hi) { unsigned r; asm volatile("v_cvt_pk_bf16_f32 %0, %1, %2" : "=v"(r) : "v"(lo), "v"(hi)); return r; }
;     DEVI void operator()(f32x4 (&acc)[2][2][4][2], const Unit& u, int wr, int wc, int fr, int fq) const {
;     ...
;                 for (int bj = 0; bj < 2; ++bj) { f32x4 v0 = acc[ai][bj][m][0], v1 = acc[ai][bj][m][1];
;                     if (RS) { v0 = v0 * rstd + sh[bj][0]; v1 = v1 * rstd + sh[bj][1]; }
;                     if (ACT == 1) {
; #pragma unroll
;                         for (int j = 0; j < 4; ++j) { const float a = fmaxf(v0[j], 0.f), b = fmaxf(v1[j], 0.f); v0[j] = a * a; v1[j] = b * b; } }
;                     if (ACT == 2) {
; #pragma unroll
;                         for (int j = 0; j < 4; ++j) { v0[j] = 1.0f + __expf(-fminf(fmaxf(v0[j], -30.f), 30.f)); v1[j] = 1.0f + __expf(-fminf(fmaxf(v1[j], -30.f), 30.f)); } }
;                     u32x4 w; w.x = cvt_pk_bf16(v0[0], v0[1]); w.y = cvt_pk_bf16(v0[2], v0[3]); w.z = cvt_pk_bf16(v1[0], v1[1]); w.w = cvt_pk_bf16(v1[2], v1[3]);
;                     *(u32x4*)(rowp + bj * HALF) = w; } }
	global_store_dwordx4 v[180:181], v[168:171], off
	v_max_f32_e32 v86, v86, v86
	v_max_f32_e32 v85, v85, v85
	v_add_f32_e32 v90, 1.0, v82
	v_max_f32_e32 v82, v87, v87
	v_add_f32_e32 v87, 1.0, v83
	v_max_f32_e32 v83, v88, v88
	v_add_f32_e32 v88, 1.0, v84
	v_max_f32_e32 v84, v89, v89
	v_med3_f32 v82, v82, s49, v238
	v_med3_f32 v83, v83, s49, v238
	v_med3_f32 v84, v84, s49, v238
	v_med3_f32 v86, v86, s49, v238
	v_mul_f32_e32 v82, 0xbfb8aa3b, v82
	v_mul_f32_e32 v83, 0xbfb8aa3b, v83
	v_mul_f32_e32 v84, 0xbfb8aa3b, v84
	v_med3_f32 v85, v85, s49, v238
	v_max_f32_e32 v74, v74, v74
	v_mul_f32_e32 v86, 0xbfb8aa3b, v86
	v_exp_f32_e32 v82, v82
	v_exp_f32_e32 v83, v83
	v_exp_f32_e32 v84, v84
	v_mul_f32_e32 v85, 0xbfb8aa3b, v85
	v_med3_f32 v74, v74, s49, v238
	v_max_f32_e32 v75, v75, v75
	v_max_f32_e32 v76, v76, v76
	v_exp_f32_e32 v86, v86
	v_exp_f32_e32 v85, v85
	v_mul_f32_e32 v74, 0xbfb8aa3b, v74
	v_med3_f32 v75, v75, s49, v238
	v_med3_f32 v76, v76, s49, v238
	v_exp_f32_e32 v74, v74
	v_mul_f32_e32 v75, 0xbfb8aa3b, v75
	v_mul_f32_e32 v76, 0xbfb8aa3b, v76
	v_exp_f32_e32 v75, v75
	v_exp_f32_e32 v76, v76
	v_add_f32_e32 v82, 1.0, v82
	v_add_f32_e32 v83, 1.0, v83
	v_add_f32_e32 v84, 1.0, v84
	v_add_f32_e32 v86, 1.0, v86
	v_add_f32_e32 v85, 1.0, v85
	v_cvt_pk_bf16_f32 v82, v86, v82
	v_cvt_pk_bf16_f32 v83, v83, v84
	v_cvt_pk_bf16_f32 v84, v90, v87
	v_cvt_pk_bf16_f32 v85, v88, v85
	ds_bpermute_b32 v164, v254, v82
	ds_bpermute_b32 v165, v254, v83
	ds_bpermute_b32 v166, v254, v84
	ds_bpermute_b32 v167, v254, v85
	v_mov_b64_e32 v[178:179], v[98:99]
	s_waitcnt lgkmcnt(8)
	global_store_dwordx4 v[182:183], v[172:175], off offset:256
	v_max_f32_e32 v78, v78, v78
	v_max_f32_e32 v77, v77, v77
	v_add_f32_e32 v84, 1.0, v74
	v_max_f32_e32 v74, v79, v79
	v_med3_f32 v74, v74, s49, v238
	v_add_f32_e32 v79, 1.0, v75
	v_max_f32_e32 v75, v80, v80
	v_add_f32_e32 v80, 1.0, v76
	v_max_f32_e32 v76, v81, v81
	v_med3_f32 v78, v78, s49, v238
	v_mul_f32_e32 v74, 0xbfb8aa3b, v74
	v_med3_f32 v75, v75, s49, v238
	v_med3_f32 v76, v76, s49, v238
	v_med3_f32 v77, v77, s49, v238
	v_max_f32_e32 v66, v66, v66
	v_max_f32_e32 v67, v67, v67
	v_max_f32_e32 v68, v68, v68
	v_mul_f32_e32 v78, 0xbfb8aa3b, v78
	v_exp_f32_e32 v74, v74
	v_mul_f32_e32 v75, 0xbfb8aa3b, v75
	v_mul_f32_e32 v76, 0xbfb8aa3b, v76
	v_mul_f32_e32 v77, 0xbfb8aa3b, v77
	v_med3_f32 v66, v66, s49, v238
	v_med3_f32 v67, v67, s49, v238
	v_med3_f32 v68, v68, s49, v238
	v_exp_f32_e32 v78, v78
	v_exp_f32_e32 v75, v75
	v_exp_f32_e32 v76, v76
	v_exp_f32_e32 v77, v77
	v_mul_f32_e32 v66, 0xbfb8aa3b, v66
	v_mul_f32_e32 v67, 0xbfb8aa3b, v67
	v_mul_f32_e32 v68, 0xbfb8aa3b, v68
	v_exp_f32_e32 v66, v66
	v_exp_f32_e32 v67, v67
	v_exp_f32_e32 v68, v68
	v_or_b32_e32 v82, 48, v148
	v_mad_i64_i32 v[82:83], s[28:29], v82, s1, v[140:141]
	v_add_f32_e32 v74, 1.0, v74
	v_lshl_add_u64 v[82:83], v[82:83], 0, v[142:143]
	v_add_f32_e32 v78, 1.0, v78
	v_add_f32_e32 v75, 1.0, v75
	v_add_f32_e32 v76, 1.0, v76
	v_add_f32_e32 v77, 1.0, v77
	v_cvt_pk_bf16_f32 v74, v78, v74
	v_cvt_pk_bf16_f32 v75, v75, v76
	v_cvt_pk_bf16_f32 v76, v84, v79
	v_cvt_pk_bf16_f32 v77, v80, v77
	ds_bpermute_b32 v168, v254, v74
	ds_bpermute_b32 v169, v254, v75
	ds_bpermute_b32 v170, v254, v76
	ds_bpermute_b32 v171, v254, v77
	v_mov_b64_e32 v[180:181], v[82:83]
	s_waitcnt lgkmcnt(8)
	global_store_dwordx4 v[176:177], v[160:163], off
	v_max_f32_e32 v70, v70, v70
	v_max_f32_e32 v69, v69, v69
	v_add_f32_e32 v74, 1.0, v66
	v_max_f32_e32 v66, v71, v71
	v_add_f32_e32 v71, 1.0, v67
	v_max_f32_e32 v67, v72, v72
	v_add_f32_e32 v72, 1.0, v68
	v_max_f32_e32 v68, v73, v73
	v_med3_f32 v66, v66, s49, v238
	v_med3_f32 v67, v67, s49, v238
	v_med3_f32 v68, v68, s49, v238
	v_med3_f32 v70, v70, s49, v238
	v_mul_f32_e32 v66, 0xbfb8aa3b, v66
	v_mul_f32_e32 v67, 0xbfb8aa3b, v67
	v_mul_f32_e32 v68, 0xbfb8aa3b, v68
	v_med3_f32 v69, v69, s49, v238
	v_max_f32_e32 v58, v58, v58
	v_mul_f32_e32 v70, 0xbfb8aa3b, v70
	v_exp_f32_e32 v66, v66
	v_exp_f32_e32 v67, v67
	v_exp_f32_e32 v68, v68
	v_mul_f32_e32 v69, 0xbfb8aa3b, v69
	v_med3_f32 v58, v58, s49, v238
	v_max_f32_e32 v59, v59, v59
	v_max_f32_e32 v60, v60, v60
	v_exp_f32_e32 v70, v70
	v_exp_f32_e32 v69, v69
	v_mul_f32_e32 v58, 0xbfb8aa3b, v58
	v_med3_f32 v59, v59, s49, v238
	v_med3_f32 v60, v60, s49, v238
	v_exp_f32_e32 v58, v58
	v_mul_f32_e32 v59, 0xbfb8aa3b, v59
	v_mul_f32_e32 v60, 0xbfb8aa3b, v60
	v_exp_f32_e32 v59, v59
	v_exp_f32_e32 v60, v60
	v_add_f32_e32 v66, 1.0, v66
	v_add_f32_e32 v67, 1.0, v67
	v_add_f32_e32 v68, 1.0, v68
	v_add_f32_e32 v70, 1.0, v70
	v_add_f32_e32 v69, 1.0, v69
	v_cvt_pk_bf16_f32 v66, v70, v66
	v_cvt_pk_bf16_f32 v67, v67, v68
	v_cvt_pk_bf16_f32 v68, v74, v71
	v_cvt_pk_bf16_f32 v69, v72, v69
	ds_bpermute_b32 v172, v254, v66
	ds_bpermute_b32 v173, v254, v67
	ds_bpermute_b32 v174, v254, v68
	ds_bpermute_b32 v175, v254, v69
	v_mov_b64_e32 v[182:183], v[82:83]
	s_waitcnt lgkmcnt(8)
; DEVI unsigned cvt_pk_bf16(float lo, float hi) { unsigned r; asm volatile("v_cvt_pk_bf16_f32 %0, %1, %2" : "=v"(r) : "v"(lo), "v"(hi)); return r; }
;     DEVI void operator()(f32x4 (&acc)[2][2][4][2], const Unit& u, int wr, int wc, int fr, int fq) const {
;     ...
;                 for (int bj = 0; bj < 2; ++bj) { f32x4 v0 = acc[ai][bj][m][0], v1 = acc[ai][bj][m][1];
;                     if (RS) { v0 = v0 * rstd + sh[bj][0]; v1 = v1 * rstd + sh[bj][1]; }
;                     if (ACT == 1) {
; #pragma unroll
;                         for (int j = 0; j < 4; ++j) { const float a = fmaxf(v0[j], 0.f), b = fmaxf(v1[j], 0.f); v0[j] = a * a; v1[j] = b * b; } }
;                     if (ACT == 2) {
; #pragma unroll
;                         for (int j = 0; j < 4; ++j) { v0[j] = 1.0f + __expf(-fminf(fmaxf(v0[j], -30.f), 30.f)); v1[j] = 1.0f + __expf(-fminf(fmaxf(v1[j], -30.f), 30.f)); } }
;                     u32x4 w; w.x = cvt_pk_bf16(v0[0], v0[1]); w.y = cvt_pk_bf16(v0[2], v0[3]); w.z = cvt_pk_bf16(v1[0], v1[1]); w.w = cvt_pk_bf16(v1[2], v1[3]);
;                     *(u32x4*)(rowp + bj * HALF) = w; } }
	global_store_dwordx4 v[178:179], v[164:167], off offset:256
	v_max_f32_e32 v62, v62, v62
	v_max_f32_e32 v61, v61, v61
	v_add_f32_e32 v68, 1.0, v58
	v_max_f32_e32 v58, v63, v63
	v_med3_f32 v58, v58, s49, v238
	v_add_f32_e32 v63, 1.0, v59
	v_max_f32_e32 v59, v64, v64
	v_add_f32_e32 v64, 1.0, v60
	v_max_f32_e32 v60, v65, v65
	v_med3_f32 v62, v62, s49, v238
	v_mul_f32_e32 v58, 0xbfb8aa3b, v58
	v_med3_f32 v59, v59, s49, v238
	v_med3_f32 v60, v60, s49, v238
	v_med3_f32 v61, v61, s49, v238
	v_max_f32_e32 v50, v50, v50
	v_max_f32_e32 v51, v51, v51
	v_max_f32_e32 v52, v52, v52
	v_mul_f32_e32 v62, 0xbfb8aa3b, v62
	v_exp_f32_e32 v58, v58
	v_mul_f32_e32 v59, 0xbfb8aa3b, v59
	v_mul_f32_e32 v60, 0xbfb8aa3b, v60
	v_mul_f32_e32 v61, 0xbfb8aa3b, v61
	v_med3_f32 v50, v50, s49, v238
	v_med3_f32 v51, v51, s49, v238
	v_med3_f32 v52, v52, s49, v238
	v_exp_f32_e32 v62, v62
	v_exp_f32_e32 v59, v59
	v_exp_f32_e32 v60, v60
	v_exp_f32_e32 v61, v61
	v_mul_f32_e32 v50, 0xbfb8aa3b, v50
	v_mul_f32_e32 v51, 0xbfb8aa3b, v51
	v_mul_f32_e32 v52, 0xbfb8aa3b, v52
	v_exp_f32_e32 v50, v50
	v_exp_f32_e32 v51, v51
	v_exp_f32_e32 v52, v52
	v_add_u32_e32 v66, 0x80, v148
	v_mad_i64_i32 v[66:67], s[28:29], v66, s1, v[140:141]
	v_add_f32_e32 v58, 1.0, v58
	v_lshl_add_u64 v[66:67], v[66:67], 0, v[142:143]
	v_add_f32_e32 v62, 1.0, v62
	v_add_f32_e32 v59, 1.0, v59
	v_add_f32_e32 v60, 1.0, v60
	v_add_f32_e32 v61, 1.0, v61
	v_cvt_pk_bf16_f32 v58, v62, v58
	v_cvt_pk_bf16_f32 v59, v59, v60
	v_cvt_pk_bf16_f32 v60, v68, v63
	v_cvt_pk_bf16_f32 v61, v64, v61
	ds_bpermute_b32 v160, v254, v58
	ds_bpermute_b32 v161, v254, v59
	ds_bpermute_b32 v162, v254, v60
	ds_bpermute_b32 v163, v254, v61
	v_mov_b64_e32 v[176:177], v[66:67]
	s_waitcnt lgkmcnt(8)
	global_store_dwordx4 v[180:181], v[168:171], off
	v_max_f32_e32 v54, v54, v54
	v_max_f32_e32 v53, v53, v53
	v_add_f32_e32 v58, 1.0, v50
	v_max_f32_e32 v50, v55, v55
	v_add_f32_e32 v55, 1.0, v51
	v_max_f32_e32 v51, v56, v56
	v_add_f32_e32 v56, 1.0, v52
	v_max_f32_e32 v52, v57, v57
	v_med3_f32 v50, v50, s49, v238
	v_med3_f32 v51, v51, s49, v238
	v_med3_f32 v52, v52, s49, v238
	v_med3_f32 v54, v54, s49, v238
	v_mul_f32_e32 v50, 0xbfb8aa3b, v50
	v_mul_f32_e32 v51, 0xbfb8aa3b, v51
	v_mul_f32_e32 v52, 0xbfb8aa3b, v52
	v_med3_f32 v53, v53, s49, v238
	v_max_f32_e32 v42, v42, v42
	v_mul_f32_e32 v54, 0xbfb8aa3b, v54
	v_exp_f32_e32 v50, v50
	v_exp_f32_e32 v51, v51
	v_exp_f32_e32 v52, v52
	v_mul_f32_e32 v53, 0xbfb8aa3b, v53
	v_med3_f32 v42, v42, s49, v238
	v_max_f32_e32 v43, v43, v43
	v_max_f32_e32 v44, v44, v44
	v_exp_f32_e32 v54, v54
	v_exp_f32_e32 v53, v53
	v_mul_f32_e32 v42, 0xbfb8aa3b, v42
	v_med3_f32 v43, v43, s49, v238
	v_med3_f32 v44, v44, s49, v238
	v_exp_f32_e32 v42, v42
	v_mul_f32_e32 v43, 0xbfb8aa3b, v43
	v_mul_f32_e32 v44, 0xbfb8aa3b, v44
	v_exp_f32_e32 v43, v43
	v_exp_f32_e32 v44, v44
	v_add_f32_e32 v50, 1.0, v50
	v_add_f32_e32 v51, 1.0, v51
	v_add_f32_e32 v52, 1.0, v52
	v_add_f32_e32 v54, 1.0, v54
	v_add_f32_e32 v53, 1.0, v53
	v_cvt_pk_bf16_f32 v50, v54, v50
	v_cvt_pk_bf16_f32 v51, v51, v52
	v_cvt_pk_bf16_f32 v52, v58, v55
	v_cvt_pk_bf16_f32 v53, v56, v53
	ds_bpermute_b32 v164, v254, v50
	ds_bpermute_b32 v165, v254, v51
	ds_bpermute_b32 v166, v254, v52
	ds_bpermute_b32 v167, v254, v53
	v_mov_b64_e32 v[178:179], v[66:67]
	s_waitcnt lgkmcnt(8)
	global_store_dwordx4 v[182:183], v[172:175], off offset:256
	v_max_f32_e32 v46, v46, v46
	v_max_f32_e32 v45, v45, v45
	v_add_f32_e32 v52, 1.0, v42
	v_max_f32_e32 v42, v47, v47
	v_med3_f32 v42, v42, s49, v238
	v_add_f32_e32 v47, 1.0, v43
	v_max_f32_e32 v43, v48, v48
	v_add_f32_e32 v48, 1.0, v44
	v_max_f32_e32 v44, v49, v49
	v_med3_f32 v46, v46, s49, v238
	v_mul_f32_e32 v42, 0xbfb8aa3b, v42
	v_med3_f32 v43, v43, s49, v238
	v_med3_f32 v44, v44, s49, v238
	v_med3_f32 v45, v45, s49, v238
	v_max_f32_e32 v34, v34, v34
	v_max_f32_e32 v35, v35, v35
	v_max_f32_e32 v36, v36, v36
	v_mul_f32_e32 v46, 0xbfb8aa3b, v46
	v_exp_f32_e32 v42, v42
	v_mul_f32_e32 v43, 0xbfb8aa3b, v43
	v_mul_f32_e32 v44, 0xbfb8aa3b, v44
	v_mul_f32_e32 v45, 0xbfb8aa3b, v45
	v_med3_f32 v34, v34, s49, v238
	v_med3_f32 v35, v35, s49, v238
	v_med3_f32 v36, v36, s49, v238
	v_exp_f32_e32 v46, v46
	v_exp_f32_e32 v43, v43
	v_exp_f32_e32 v44, v44
	v_exp_f32_e32 v45, v45
	v_mul_f32_e32 v34, 0xbfb8aa3b, v34
	v_mul_f32_e32 v35, 0xbfb8aa3b, v35
	v_mul_f32_e32 v36, 0xbfb8aa3b, v36
	v_exp_f32_e32 v34, v34
	v_exp_f32_e32 v35, v35
	v_exp_f32_e32 v36, v36
	v_add_u32_e32 v50, 0x90, v148
	v_mad_i64_i32 v[50:51], s[28:29], v50, s1, v[140:141]
	v_add_f32_e32 v42, 1.0, v42
	v_lshl_add_u64 v[50:51], v[50:51], 0, v[142:143]
	v_add_f32_e32 v46, 1.0, v46
	v_add_f32_e32 v43, 1.0, v43
	v_add_f32_e32 v44, 1.0, v44
	v_add_f32_e32 v45, 1.0, v45
	v_cvt_pk_bf16_f32 v42, v46, v42
	v_cvt_pk_bf16_f32 v43, v43, v44
	v_cvt_pk_bf16_f32 v44, v52, v47
	v_cvt_pk_bf16_f32 v45, v48, v45
	ds_bpermute_b32 v168, v254, v42
	ds_bpermute_b32 v169, v254, v43
	ds_bpermute_b32 v170, v254, v44
	ds_bpermute_b32 v171, v254, v45
	v_mov_b64_e32 v[180:181], v[50:51]
	s_waitcnt lgkmcnt(8)
; DEVI unsigned cvt_pk_bf16(float lo, float hi) { unsigned r; asm volatile("v_cvt_pk_bf16_f32 %0, %1, %2" : "=v"(r) : "v"(lo), "v"(hi)); return r; }
;     DEVI void operator()(f32x4 (&acc)[2][2][4][2], const Unit& u, int wr, int wc, int fr, int fq) const {
;     ...
;                 for (int bj = 0; bj < 2; ++bj) { f32x4 v0 = acc[ai][bj][m][0], v1 = acc[ai][bj][m][1];
;                     if (RS) { v0 = v0 * rstd + sh[bj][0]; v1 = v1 * rstd + sh[bj][1]; }
;                     if (ACT == 1) {
; #pragma unroll
;                         for (int j = 0; j < 4; ++j) { const float a = fmaxf(v0[j], 0.f), b = fmaxf(v1[j], 0.f); v0[j] = a * a; v1[j] = b * b; } }
;                     if (ACT == 2) {
; #pragma unroll
;                         for (int j = 0; j < 4; ++j) { v0[j] = 1.0f + __expf(-fminf(fmaxf(v0[j], -30.f), 30.f)); v1[j] = 1.0f + __expf(-fminf(fmaxf(v1[j], -30.f), 30.f)); } }
;                     u32x4 w; w.x = cvt_pk_bf16(v0[0], v0[1]); w.y = cvt_pk_bf16(v0[2], v0[3]); w.z = cvt_pk_bf16(v1[0], v1[1]); w.w = cvt_pk_bf16(v1[2], v1[3]);
;                     *(u32x4*)(rowp + bj * HALF) = w; } }
	global_store_dwordx4 v[176:177], v[160:163], off
	v_max_f32_e32 v38, v38, v38
	v_max_f32_e32 v37, v37, v37
	v_add_f32_e32 v42, 1.0, v34
	v_max_f32_e32 v34, v39, v39
	v_add_f32_e32 v39, 1.0, v35
	v_max_f32_e32 v35, v40, v40
	v_add_f32_e32 v40, 1.0, v36
	v_max_f32_e32 v36, v41, v41
	v_med3_f32 v34, v34, s49, v238
	v_med3_f32 v35, v35, s49, v238
	v_med3_f32 v36, v36, s49, v238
	v_med3_f32 v38, v38, s49, v238
	v_mul_f32_e32 v34, 0xbfb8aa3b, v34
	v_mul_f32_e32 v35, 0xbfb8aa3b, v35
	v_mul_f32_e32 v36, 0xbfb8aa3b, v36
	v_med3_f32 v37, v37, s49, v238
	v_max_f32_e32 v26, v26, v26
	v_mul_f32_e32 v38, 0xbfb8aa3b, v38
	v_exp_f32_e32 v34, v34
	v_exp_f32_e32 v35, v35
	v_exp_f32_e32 v36, v36
	v_mul_f32_e32 v37, 0xbfb8aa3b, v37
	v_med3_f32 v26, v26, s49, v238
	v_max_f32_e32 v27, v27, v27
	v_max_f32_e32 v28, v28, v28
	v_exp_f32_e32 v38, v38
	v_exp_f32_e32 v37, v37
	v_mul_f32_e32 v26, 0xbfb8aa3b, v26
	v_med3_f32 v27, v27, s49, v238
	v_med3_f32 v28, v28, s49, v238
	v_exp_f32_e32 v26, v26
	v_mul_f32_e32 v27, 0xbfb8aa3b, v27
	v_mul_f32_e32 v28, 0xbfb8aa3b, v28
	v_exp_f32_e32 v27, v27
	v_exp_f32_e32 v28, v28
	v_add_f32_e32 v34, 1.0, v34
	v_add_f32_e32 v35, 1.0, v35
	v_add_f32_e32 v36, 1.0, v36
	v_add_f32_e32 v38, 1.0, v38
	v_add_f32_e32 v37, 1.0, v37
	v_cvt_pk_bf16_f32 v34, v38, v34
	v_cvt_pk_bf16_f32 v35, v35, v36
	v_cvt_pk_bf16_f32 v36, v42, v39
	v_cvt_pk_bf16_f32 v37, v40, v37
	ds_bpermute_b32 v172, v254, v34
	ds_bpermute_b32 v173, v254, v35
	ds_bpermute_b32 v174, v254, v36
	ds_bpermute_b32 v175, v254, v37
	v_mov_b64_e32 v[182:183], v[50:51]
	s_waitcnt lgkmcnt(8)
	global_store_dwordx4 v[178:179], v[164:167], off offset:256
	v_max_f32_e32 v30, v30, v30
	v_max_f32_e32 v29, v29, v29
	v_add_f32_e32 v36, 1.0, v26
	v_max_f32_e32 v26, v31, v31
	v_med3_f32 v26, v26, s49, v238
	v_add_f32_e32 v31, 1.0, v27
	v_max_f32_e32 v27, v32, v32
	v_add_f32_e32 v32, 1.0, v28
	v_max_f32_e32 v28, v33, v33
	v_med3_f32 v30, v30, s49, v238
	v_mul_f32_e32 v26, 0xbfb8aa3b, v26
	v_med3_f32 v27, v27, s49, v238
	v_med3_f32 v28, v28, s49, v238
	v_med3_f32 v29, v29, s49, v238
	v_max_f32_e32 v18, v18, v18
	v_max_f32_e32 v19, v19, v19
	v_max_f32_e32 v20, v20, v20
	v_mul_f32_e32 v30, 0xbfb8aa3b, v30
	v_exp_f32_e32 v26, v26
	v_mul_f32_e32 v27, 0xbfb8aa3b, v27
	v_mul_f32_e32 v28, 0xbfb8aa3b, v28
	v_mul_f32_e32 v29, 0xbfb8aa3b, v29
	v_med3_f32 v18, v18, s49, v238
	v_med3_f32 v19, v19, s49, v238
	v_med3_f32 v20, v20, s49, v238
	v_exp_f32_e32 v30, v30
	v_exp_f32_e32 v27, v27
	v_exp_f32_e32 v28, v28
	v_exp_f32_e32 v29, v29
	v_mul_f32_e32 v18, 0xbfb8aa3b, v18
	v_mul_f32_e32 v19, 0xbfb8aa3b, v19
	v_mul_f32_e32 v20, 0xbfb8aa3b, v20
	v_exp_f32_e32 v18, v18
	v_exp_f32_e32 v19, v19
	v_exp_f32_e32 v20, v20
	v_add_u32_e32 v34, 0xa0, v148
	v_mad_i64_i32 v[34:35], s[28:29], v34, s1, v[140:141]
	v_add_f32_e32 v26, 1.0, v26
	v_lshl_add_u64 v[34:35], v[34:35], 0, v[142:143]
	v_add_f32_e32 v30, 1.0, v30
	v_add_f32_e32 v27, 1.0, v27
	v_add_f32_e32 v28, 1.0, v28
	v_add_f32_e32 v29, 1.0, v29
	v_cvt_pk_bf16_f32 v26, v30, v26
	v_cvt_pk_bf16_f32 v27, v27, v28
	v_cvt_pk_bf16_f32 v28, v36, v31
	v_cvt_pk_bf16_f32 v29, v32, v29
	ds_bpermute_b32 v160, v254, v26
	ds_bpermute_b32 v161, v254, v27
	ds_bpermute_b32 v162, v254, v28
	ds_bpermute_b32 v163, v254, v29
	v_mov_b64_e32 v[176:177], v[34:35]
	s_waitcnt lgkmcnt(8)
; DEVI unsigned cvt_pk_bf16(float lo, float hi) { unsigned r; asm volatile("v_cvt_pk_bf16_f32 %0, %1, %2" : "=v"(r) : "v"(lo), "v"(hi)); return r; }
;     DEVI void operator()(f32x4 (&acc)[2][2][4][2], const Unit& u, int wr, int wc, int fr, int fq) const {
;     ...
;                 for (int bj = 0; bj < 2; ++bj) { f32x4 v0 = acc[ai][bj][m][0], v1 = acc[ai][bj][m][1];
;                     if (RS) { v0 = v0 * rstd + sh[bj][0]; v1 = v1 * rstd + sh[bj][1]; }
;                     if (ACT == 1) {
; #pragma unroll
;                         for (int j = 0; j < 4; ++j) { const float a = fmaxf(v0[j], 0.f), b = fmaxf(v1[j], 0.f); v0[j] = a * a; v1[j] = b * b; } }
;                     if (ACT == 2) {
; #pragma unroll
;                         for (int j = 0; j < 4; ++j) { v0[j] = 1.0f + __expf(-fminf(fmaxf(v0[j], -30.f), 30.f)); v1[j] = 1.0f + __expf(-fminf(fmaxf(v1[j], -30.f), 30.f)); } }
;                     u32x4 w; w.x = cvt_pk_bf16(v0[0], v0[1]); w.y = cvt_pk_bf16(v0[2], v0[3]); w.z = cvt_pk_bf16(v1[0], v1[1]); w.w = cvt_pk_bf16(v1[2], v1[3]);
;                     *(u32x4*)(rowp + bj * HALF) = w; } }
; template <class Epi>
; DEVI void gemm_phase(const int wv, LAS unsigned char* lds, const Gemm g, const Order& S, const Epi& E) {
;     ...
;         if (!has_next) break;
;         cur = nxt; cA = nA; cB = nB; ++ui;
	global_store_dwordx4 v[180:181], v[168:171], off
	v_max_f32_e32 v22, v22, v22
	v_max_f32_e32 v21, v21, v21
	v_add_f32_e32 v26, 1.0, v18
	v_max_f32_e32 v18, v23, v23
	v_add_f32_e32 v23, 1.0, v19
	v_max_f32_e32 v19, v24, v24
	v_add_f32_e32 v24, 1.0, v20
	v_max_f32_e32 v20, v25, v25
	v_med3_f32 v18, v18, s49, v238
	v_med3_f32 v19, v19, s49, v238
	v_med3_f32 v20, v20, s49, v238
	v_med3_f32 v22, v22, s49, v238
	v_mul_f32_e32 v18, 0xbfb8aa3b, v18
	v_mul_f32_e32 v19, 0xbfb8aa3b, v19
	v_mul_f32_e32 v20, 0xbfb8aa3b, v20
	v_med3_f32 v21, v21, s49, v238
	v_max_f32_e32 v10, v10, v10
	v_mul_f32_e32 v22, 0xbfb8aa3b, v22
	v_exp_f32_e32 v18, v18
	v_exp_f32_e32 v19, v19
	v_exp_f32_e32 v20, v20
	v_mul_f32_e32 v21, 0xbfb8aa3b, v21
	v_med3_f32 v10, v10, s49, v238
	v_max_f32_e32 v11, v11, v11
	v_max_f32_e32 v12, v12, v12
	v_exp_f32_e32 v22, v22
	v_exp_f32_e32 v21, v21
	v_mul_f32_e32 v10, 0xbfb8aa3b, v10
	v_med3_f32 v11, v11, s49, v238
	v_med3_f32 v12, v12, s49, v238
	v_exp_f32_e32 v10, v10
	v_mul_f32_e32 v11, 0xbfb8aa3b, v11
	v_mul_f32_e32 v12, 0xbfb8aa3b, v12
	v_exp_f32_e32 v11, v11
	v_exp_f32_e32 v12, v12
	v_add_f32_e32 v18, 1.0, v18
	v_add_f32_e32 v19, 1.0, v19
	v_add_f32_e32 v20, 1.0, v20
	v_add_f32_e32 v22, 1.0, v22
	v_add_f32_e32 v21, 1.0, v21
	v_cvt_pk_bf16_f32 v18, v22, v18
	v_cvt_pk_bf16_f32 v19, v19, v20
	v_cvt_pk_bf16_f32 v20, v26, v23
	v_cvt_pk_bf16_f32 v21, v24, v21
	ds_bpermute_b32 v164, v254, v18
	ds_bpermute_b32 v165, v254, v19
	ds_bpermute_b32 v166, v254, v20
	ds_bpermute_b32 v167, v254, v21
	v_mov_b64_e32 v[178:179], v[34:35]
	s_waitcnt lgkmcnt(8)
	global_store_dwordx4 v[182:183], v[172:175], off offset:256
	v_max_f32_e32 v14, v14, v14
	v_max_f32_e32 v13, v13, v13
	v_add_f32_e32 v20, 1.0, v10
	v_max_f32_e32 v10, v15, v15
	v_med3_f32 v10, v10, s49, v238
	v_add_f32_e32 v15, 1.0, v11
	v_max_f32_e32 v11, v16, v16
	v_add_f32_e32 v16, 1.0, v12
	v_max_f32_e32 v12, v17, v17
	v_med3_f32 v14, v14, s49, v238
	v_mul_f32_e32 v10, 0xbfb8aa3b, v10
	v_med3_f32 v11, v11, s49, v238
	v_med3_f32 v12, v12, s49, v238
	v_med3_f32 v13, v13, s49, v238
	v_max_f32_e32 v2, v2, v2
	v_max_f32_e32 v3, v3, v3
	v_max_f32_e32 v4, v4, v4
	v_mul_f32_e32 v14, 0xbfb8aa3b, v14
	v_exp_f32_e32 v10, v10
	v_mul_f32_e32 v11, 0xbfb8aa3b, v11
	v_mul_f32_e32 v12, 0xbfb8aa3b, v12
	v_mul_f32_e32 v13, 0xbfb8aa3b, v13
	v_med3_f32 v2, v2, s49, v238
	v_med3_f32 v3, v3, s49, v238
	v_med3_f32 v4, v4, s49, v238
	v_exp_f32_e32 v14, v14
	v_exp_f32_e32 v11, v11
	v_exp_f32_e32 v12, v12
	v_exp_f32_e32 v13, v13
	v_mul_f32_e32 v2, 0xbfb8aa3b, v2
	v_mul_f32_e32 v3, 0xbfb8aa3b, v3
	v_mul_f32_e32 v4, 0xbfb8aa3b, v4
	v_exp_f32_e32 v2, v2
	v_exp_f32_e32 v3, v3
	v_exp_f32_e32 v4, v4
	v_add_u32_e32 v18, 0xb0, v148
	v_mad_i64_i32 v[18:19], s[28:29], v18, s1, v[140:141]
	v_add_f32_e32 v10, 1.0, v10
	v_lshl_add_u64 v[18:19], v[18:19], 0, v[142:143]
	v_add_f32_e32 v14, 1.0, v14
	v_add_f32_e32 v11, 1.0, v11
	v_add_f32_e32 v12, 1.0, v12
	v_add_f32_e32 v13, 1.0, v13
	v_cvt_pk_bf16_f32 v10, v14, v10
	v_cvt_pk_bf16_f32 v11, v11, v12
	v_cvt_pk_bf16_f32 v12, v20, v15
	v_cvt_pk_bf16_f32 v13, v16, v13
	ds_bpermute_b32 v168, v254, v10
	ds_bpermute_b32 v169, v254, v11
	ds_bpermute_b32 v170, v254, v12
	ds_bpermute_b32 v171, v254, v13
	v_mov_b64_e32 v[180:181], v[18:19]
	s_waitcnt lgkmcnt(8)
	global_store_dwordx4 v[176:177], v[160:163], off
	v_max_f32_e32 v5, v5, v5
	v_max_f32_e32 v6, v6, v6
	v_add_f32_e32 v10, 1.0, v2
	v_max_f32_e32 v2, v7, v7
	v_add_f32_e32 v7, 1.0, v3
	v_max_f32_e32 v3, v8, v8
	v_add_f32_e32 v8, 1.0, v4
	v_max_f32_e32 v4, v9, v9
	v_med3_f32 v2, v2, s49, v238
	v_med3_f32 v3, v3, s49, v238
	v_med3_f32 v4, v4, s49, v238
	v_med3_f32 v5, v5, s49, v238
	v_med3_f32 v6, v6, s49, v238
	v_mul_f32_e32 v2, 0xbfb8aa3b, v2
	v_mul_f32_e32 v3, 0xbfb8aa3b, v3
	v_mul_f32_e32 v4, 0xbfb8aa3b, v4
	v_mul_f32_e32 v5, 0xbfb8aa3b, v5
	v_mul_f32_e32 v6, 0xbfb8aa3b, v6
	v_exp_f32_e32 v2, v2
	v_exp_f32_e32 v3, v3
	v_exp_f32_e32 v4, v4
	v_exp_f32_e32 v5, v5
	v_exp_f32_e32 v6, v6
	s_movk_i32 s47, 0x1800
	v_add_f32_e32 v2, 1.0, v2
	v_add_f32_e32 v3, 1.0, v3
	v_add_f32_e32 v4, 1.0, v4
	v_add_f32_e32 v5, 1.0, v5
	s_and_b64 vcc, exec, s[6:7]
	s_mov_b32 s10, s0
	s_mov_b32 s12, s2
	s_mov_b64 s[30:31], s[8:9]
	s_mov_b64 s[28:29], s[4:5]
	s_movk_i32 s55, 0xc00
	v_add_f32_e32 v6, 1.0, v6
	v_cvt_pk_bf16_f32 v2, v6, v2
	v_cvt_pk_bf16_f32 v3, v3, v4
	v_cvt_pk_bf16_f32 v4, v10, v7
	v_cvt_pk_bf16_f32 v5, v8, v5
	ds_bpermute_b32 v172, v254, v2
	ds_bpermute_b32 v173, v254, v3
	ds_bpermute_b32 v174, v254, v4
	ds_bpermute_b32 v175, v254, v5
	v_mov_b64_e32 v[182:183], v[18:19]
	s_waitcnt lgkmcnt(8)
	global_store_dwordx4 v[178:179], v[164:167], off offset:256
	s_waitcnt lgkmcnt(4)
	global_store_dwordx4 v[180:181], v[168:171], off
	s_waitcnt lgkmcnt(0)
	global_store_dwordx4 v[182:183], v[172:175], off offset:256
	s_cbranch_vccz .LBB0_809
	s_branch .LBB0_817
